# v112 + GEMM K-loops: the second s_waitcnt lgkmcnt(0) after each phase barrier removed (no LDS op is issued between the two)
# baseline (speedup 1.0000x reference)
; #define PG8_STAGE(bufoff, gbase, voff) do { _Pragma("unroll") for (int _i = 0; _i < 2; ++_i) \
;         __builtin_amdgcn_global_load_lds((const unsigned*)((const char*)(gbase) + (voff)[_i]), (PG8_LAS unsigned*)(lds + (bufoff) + ldsw + _i * 8192), 16, 0, 0); } while (0)
; #define PG8_LDA(dst, b, h) do { _Pragma("unroll") for (int m = 0; m < 4; ++m) _Pragma("unroll") for (int k = 0; k < 2; ++k) dst[m][k] = *(const PG8_LAS bf16x8*)(lds + PG8_SA(b, h) + aoff + m * 2048 + k * 1024); } while (0)
; #define PG8_LDB(dst, b, h) do { _Pragma("unroll") for (int n = 0; n < 2; ++n) _Pragma("unroll") for (int k = 0; k < 2; ++k) dst[n][k] = *(const PG8_LAS bf16x8*)(lds + PG8_SB(b, h) + boff + n * 2048 + k * 1024); } while (0)
; #define PG8_MMA(ai, bj, At, Bt) do { __builtin_amdgcn_s_setprio(1); _Pragma("unroll") for (int m = 0; m < 4; ++m) _Pragma("unroll") for (int n = 0; n < 2; ++n) _Pragma("unroll") for (int k = 0; k < 2; ++k) \
;         acc[ai][bj][m][n] = __builtin_amdgcn_mfma_f32_16x16x32_bf16(Bt[n][k], At[m][k], acc[ai][bj][m][n], 0, 0, 0); __builtin_amdgcn_s_setprio(0); } while (0)
; #define PG8_WAIT_V(n) asm volatile("s_waitcnt vmcnt(" #n ")" ::: "memory")
; #define PG8_WAIT_L(n) asm volatile("s_waitcnt lgkmcnt(" #n ")" ::: "memory")
; #define PG8_BAR __builtin_amdgcn_s_barrier()
; #define PG8_SCHED __builtin_amdgcn_sched_barrier(0)
; template <class Epi, class Sched, bool ALIGN_EPI = false, bool SP2 = false>
; __device__ __forceinline__ void gemm_phase(PG8_LAS unsigned char* lds, const Gemm g, const Sched& S, const Epi& E) {
;     ...
;             PG8_LDB(B0, 0, 0); PG8_LDB(B1, 0, 1); PG8_SCHED; PG8_LDA(At, 0, 0); PG8_STAGE(PG8_SA(1, 1), a1 + hstep, voffA);
;             PG8_WAIT_V(8); PG8_WAIT_L(0); PG8_BAR; PG8_MMA(0, 0, At, B0); PG8_MMA(0, 1, At, B1); PG8_BAR; PG8_SCHED;
;             PG8_LDA(At, 0, 1); PG8_STAGE(PG8_SB(0, 0), b2, voffB); PG8_STAGE(PG8_SB(0, 1), b2 + hstep, voffB); PG8_STAGE(PG8_SA(0, 0), a2, voffA);
;             PG8_WAIT_V(8); PG8_WAIT_L(0); PG8_BAR; PG8_MMA(1, 0, At, B0); PG8_MMA(1, 1, At, B1); PG8_BAR; PG8_SCHED;
.LBB0_119:
	ds_read_b128 v[56:59], v167
	ds_read_b128 v[60:63], v167 offset:1024
	ds_read_b128 v[136:139], v167 offset:2048
	ds_read_b128 v[158:161], v167 offset:3072
	ds_read_b128 v[170:173], v168
	ds_read_b128 v[174:177], v168 offset:1024
	ds_read_b128 v[178:181], v168 offset:2048
	ds_read_b128 v[182:185], v168 offset:3072
	s_add_u32 s26, s24, 0xfffc0080
	s_addc_u32 s27, s25, -1
	s_cmp_eq_u32 s50, 12
	s_cselect_b32 s29, s5, s27
	s_cselect_b32 s28, s7, s26
	s_cselect_b32 s27, s17, s37
	s_cselect_b32 s26, s19, s36
	s_add_u32 vcc_lo, s26, 0x80
	s_addc_u32 vcc_hi, s27, 0
	s_add_u32 s100, s28, 0x80
	s_addc_u32 s101, s29, 0
	s_add_i32 m0, s31, 0xc000
	ds_read_b128 v[186:189], v169
	ds_read_b128 v[194:197], v169 offset:1024
	ds_read_b128 v[198:201], v169 offset:2048
	ds_read_b128 v[202:205], v169 offset:3072
	ds_read_b128 v[206:209], v169 offset:4096
	ds_read_b128 v[210:213], v169 offset:5120
	ds_read_b128 v[214:217], v169 offset:6144
	global_load_lds_dwordx4 v150, s[24:25]
	s_add_i32 m0, s31, 0xe000
	ds_read_b128 v[218:221], v169 offset:7168
	global_load_lds_dwordx4 v152, s[24:25]
	s_waitcnt vmcnt(8)
	s_waitcnt lgkmcnt(0)
	s_barrier
	s_setprio 1
	v_mfma_f32_16x16x32_bf16 v[132:135], v[56:59], v[186:189], v[132:135]
	v_mfma_f32_16x16x32_bf16 v[128:131], v[136:139], v[186:189], v[128:131]
	v_mfma_f32_16x16x32_bf16 v[116:119], v[56:59], v[198:201], v[116:119]
	v_mfma_f32_16x16x32_bf16 v[112:115], v[136:139], v[198:201], v[112:115]
	v_mfma_f32_16x16x32_bf16 v[100:103], v[56:59], v[206:209], v[100:103]
	v_mfma_f32_16x16x32_bf16 v[96:99], v[136:139], v[206:209], v[96:99]
	v_mfma_f32_16x16x32_bf16 v[84:87], v[56:59], v[214:217], v[84:87]
	v_mfma_f32_16x16x32_bf16 v[80:83], v[136:139], v[214:217], v[80:83]
	v_mfma_f32_16x16x32_bf16 v[132:135], v[60:63], v[194:197], v[132:135]
	v_mfma_f32_16x16x32_bf16 v[128:131], v[158:161], v[194:197], v[128:131]
	v_mfma_f32_16x16x32_bf16 v[116:119], v[60:63], v[202:205], v[116:119]
	v_mfma_f32_16x16x32_bf16 v[112:115], v[158:161], v[202:205], v[112:115]
	v_mfma_f32_16x16x32_bf16 v[100:103], v[60:63], v[210:213], v[100:103]
	v_mfma_f32_16x16x32_bf16 v[96:99], v[158:161], v[210:213], v[96:99]
	v_mfma_f32_16x16x32_bf16 v[84:87], v[60:63], v[218:221], v[84:87]
	v_mfma_f32_16x16x32_bf16 v[80:83], v[158:161], v[218:221], v[80:83]
	s_setprio 0
	s_setprio 1
	v_mfma_f32_16x16x32_bf16 v[124:127], v[170:173], v[186:189], v[124:127]
	v_mfma_f32_16x16x32_bf16 v[120:123], v[178:181], v[186:189], v[120:123]
	v_mfma_f32_16x16x32_bf16 v[108:111], v[170:173], v[198:201], v[108:111]
	v_mfma_f32_16x16x32_bf16 v[104:107], v[178:181], v[198:201], v[104:107]
	v_mfma_f32_16x16x32_bf16 v[92:95], v[170:173], v[206:209], v[92:95]
	v_mfma_f32_16x16x32_bf16 v[88:91], v[178:181], v[206:209], v[88:91]
	v_mfma_f32_16x16x32_bf16 v[76:79], v[170:173], v[214:217], v[76:79]
	v_mfma_f32_16x16x32_bf16 v[72:75], v[178:181], v[214:217], v[72:75]
	v_mfma_f32_16x16x32_bf16 v[124:127], v[174:177], v[194:197], v[124:127]
	v_mfma_f32_16x16x32_bf16 v[120:123], v[182:185], v[194:197], v[120:123]
	v_mfma_f32_16x16x32_bf16 v[108:111], v[174:177], v[202:205], v[108:111]
	v_mfma_f32_16x16x32_bf16 v[104:107], v[182:185], v[202:205], v[104:107]
	v_mfma_f32_16x16x32_bf16 v[92:95], v[174:177], v[210:213], v[92:95]
	v_mfma_f32_16x16x32_bf16 v[88:91], v[182:185], v[210:213], v[88:91]
	v_mfma_f32_16x16x32_bf16 v[76:79], v[174:177], v[218:221], v[76:79]
	v_mfma_f32_16x16x32_bf16 v[72:75], v[182:185], v[218:221], v[72:75]
	s_setprio 0
	s_barrier
	s_add_i32 s51, s88, s58
	s_mov_b32 m0, s51
	ds_read_b128 v[186:189], v169 offset:16384
	ds_read_b128 v[194:197], v169 offset:17408
	ds_read_b128 v[198:201], v169 offset:18432
	ds_read_b128 v[202:205], v169 offset:19456
	global_load_lds_dwordx4 v142, s[26:27]
	s_add_i32 m0, s51, 0x2000
	s_add_u32 s76, s26, 0x40000
	s_addc_u32 s77, s27, 0
	s_add_i32 s51, s89, s58
	global_load_lds_dwordx4 v146, s[26:27]
	s_mov_b32 m0, s51
	ds_read_b128 v[218:221], v169 offset:23552
	global_load_lds_dwordx4 v142, s[76:77]
	s_add_i32 m0, s51, 0x2000
	ds_read_b128 v[214:217], v169 offset:22528
	global_load_lds_dwordx4 v146, s[76:77]
	s_mov_b32 m0, s31
	ds_read_b128 v[210:213], v169 offset:21504
	global_load_lds_dwordx4 v140, s[28:29]
	s_mov_b32 m0, s0
	ds_read_b128 v[206:209], v169 offset:20480
	global_load_lds_dwordx4 v144, s[28:29]
	s_waitcnt vmcnt(8)
	s_waitcnt lgkmcnt(0)
	s_barrier
	s_setprio 1
	v_mfma_f32_16x16x32_bf16 v[68:71], v[56:59], v[186:189], v[68:71]
	v_mfma_f32_16x16x32_bf16 v[64:67], v[136:139], v[186:189], v[64:67]
	v_mfma_f32_16x16x32_bf16 v[44:47], v[56:59], v[198:201], v[44:47]
	v_mfma_f32_16x16x32_bf16 v[40:43], v[136:139], v[198:201], v[40:43]
	v_mfma_f32_16x16x32_bf16 v[28:31], v[56:59], v[206:209], v[28:31]
	v_mfma_f32_16x16x32_bf16 v[24:27], v[136:139], v[206:209], v[24:27]
	v_mfma_f32_16x16x32_bf16 v[12:15], v[56:59], v[214:217], v[12:15]
	v_mfma_f32_16x16x32_bf16 v[8:11], v[136:139], v[214:217], v[8:11]
	v_mfma_f32_16x16x32_bf16 v[68:71], v[60:63], v[194:197], v[68:71]
	v_mfma_f32_16x16x32_bf16 v[64:67], v[158:161], v[194:197], v[64:67]
	v_mfma_f32_16x16x32_bf16 v[44:47], v[60:63], v[202:205], v[44:47]
	v_mfma_f32_16x16x32_bf16 v[40:43], v[158:161], v[202:205], v[40:43]
	v_mfma_f32_16x16x32_bf16 v[28:31], v[60:63], v[210:213], v[28:31]
	v_mfma_f32_16x16x32_bf16 v[24:27], v[158:161], v[210:213], v[24:27]
	v_mfma_f32_16x16x32_bf16 v[12:15], v[60:63], v[218:221], v[12:15]
	v_mfma_f32_16x16x32_bf16 v[8:11], v[158:161], v[218:221], v[8:11]
	s_setprio 0
	s_setprio 1
	v_mfma_f32_16x16x32_bf16 v[52:55], v[170:173], v[186:189], v[52:55]
	v_mfma_f32_16x16x32_bf16 v[48:51], v[178:181], v[186:189], v[48:51]
	v_mfma_f32_16x16x32_bf16 v[36:39], v[170:173], v[198:201], v[36:39]
	v_mfma_f32_16x16x32_bf16 v[32:35], v[178:181], v[198:201], v[32:35]
	v_mfma_f32_16x16x32_bf16 v[20:23], v[170:173], v[206:209], v[20:23]
	v_mfma_f32_16x16x32_bf16 v[16:19], v[178:181], v[206:209], v[16:19]
	v_mfma_f32_16x16x32_bf16 v[4:7], v[170:173], v[214:217], v[4:7]
	v_mfma_f32_16x16x32_bf16 v[0:3], v[178:181], v[214:217], v[0:3]
	v_mfma_f32_16x16x32_bf16 v[52:55], v[174:177], v[194:197], v[52:55]
	v_mfma_f32_16x16x32_bf16 v[48:51], v[182:185], v[194:197], v[48:51]
	v_mfma_f32_16x16x32_bf16 v[36:39], v[174:177], v[202:205], v[36:39]
	v_mfma_f32_16x16x32_bf16 v[32:35], v[182:185], v[202:205], v[32:35]
	v_mfma_f32_16x16x32_bf16 v[20:23], v[174:177], v[210:213], v[20:23]
	v_mfma_f32_16x16x32_bf16 v[16:19], v[182:185], v[210:213], v[16:19]
	v_mfma_f32_16x16x32_bf16 v[4:7], v[174:177], v[218:221], v[4:7]
	v_mfma_f32_16x16x32_bf16 v[0:3], v[182:185], v[218:221], v[0:3]
	s_setprio 0
	s_barrier
; #define PG8_STAGE(bufoff, gbase, voff) do { _Pragma("unroll") for (int _i = 0; _i < 2; ++_i) \
;         __builtin_amdgcn_global_load_lds((const unsigned*)((const char*)(gbase) + (voff)[_i]), (PG8_LAS unsigned*)(lds + (bufoff) + ldsw + _i * 8192), 16, 0, 0); } while (0)
; #define PG8_LDA(dst, b, h) do { _Pragma("unroll") for (int m = 0; m < 4; ++m) _Pragma("unroll") for (int k = 0; k < 2; ++k) dst[m][k] = *(const PG8_LAS bf16x8*)(lds + PG8_SA(b, h) + aoff + m * 2048 + k * 1024); } while (0)
; #define PG8_LDB(dst, b, h) do { _Pragma("unroll") for (int n = 0; n < 2; ++n) _Pragma("unroll") for (int k = 0; k < 2; ++k) dst[n][k] = *(const PG8_LAS bf16x8*)(lds + PG8_SB(b, h) + boff + n * 2048 + k * 1024); } while (0)
; #define PG8_MMA(ai, bj, At, Bt) do { __builtin_amdgcn_s_setprio(1); _Pragma("unroll") for (int m = 0; m < 4; ++m) _Pragma("unroll") for (int n = 0; n < 2; ++n) _Pragma("unroll") for (int k = 0; k < 2; ++k) \
;         acc[ai][bj][m][n] = __builtin_amdgcn_mfma_f32_16x16x32_bf16(Bt[n][k], At[m][k], acc[ai][bj][m][n], 0, 0, 0); __builtin_amdgcn_s_setprio(0); } while (0)
; #define PG8_WAIT_V(n) asm volatile("s_waitcnt vmcnt(" #n ")" ::: "memory")
; #define PG8_WAIT_L(n) asm volatile("s_waitcnt lgkmcnt(" #n ")" ::: "memory")
; #define PG8_BAR __builtin_amdgcn_s_barrier()
; #define PG8_SCHED __builtin_amdgcn_sched_barrier(0)
; template <class Epi, class Sched, bool ALIGN_EPI = false, bool SP2 = false>
; __device__ __forceinline__ void gemm_phase(PG8_LAS unsigned char* lds, const Gemm g, const Sched& S, const Epi& E) {
;     ...
;             PG8_LDB(B0, 1, 0); PG8_LDB(B1, 1, 1); PG8_SCHED; PG8_LDA(At, 1, 0); PG8_STAGE(PG8_SA(0, 1), a2 + hstep, voffA);
;             PG8_WAIT_V(8); PG8_WAIT_L(0); PG8_BAR; PG8_MMA(0, 0, At, B0); PG8_MMA(0, 1, At, B1); PG8_BAR; PG8_SCHED;
;             PG8_LDA(At, 1, 1); PG8_STAGE(PG8_SB(1, 0), b3, voffB); PG8_STAGE(PG8_SB(1, 1), b3 + hstep, voffB); PG8_STAGE(PG8_SA(1, 0), a3, voffA);
;             PG8_WAIT_V(8); PG8_WAIT_L(0); PG8_BAR; PG8_MMA(1, 0, At, B0); PG8_MMA(1, 1, At, B1); PG8_BAR; PG8_SCHED;
;     ...
;         if constexpr (ALIGN_EPI) { if (wr == 0) PG8_BAR; }
	s_add_i32 s51, 0, 0x18000
	s_add_i32 s76, 0, 0x1c000
	ds_read_b128 v[56:59], v240
	ds_read_b128 v[60:63], v240 offset:1024
	ds_read_b128 v[136:139], v240 offset:2048
	ds_read_b128 v[158:161], v240 offset:3072
	ds_read_b128 v[170:173], v241
	ds_read_b128 v[174:177], v241 offset:1024
	ds_read_b128 v[178:181], v241 offset:2048
	ds_read_b128 v[182:185], v241 offset:3072
	s_add_u32 s28, s28, 0x40000
	s_addc_u32 s29, s29, 0
	s_mov_b32 m0, s1
	ds_read_b128 v[186:189], v169 offset:32768
	ds_read_b128 v[194:197], v169 offset:33792
	ds_read_b128 v[198:201], v169 offset:34816
	ds_read_b128 v[202:205], v169 offset:35840
	ds_read_b128 v[206:209], v169 offset:36864
	ds_read_b128 v[210:213], v169 offset:37888
	ds_read_b128 v[214:217], v169 offset:38912
	global_load_lds_dwordx4 v140, s[28:29]
	s_mov_b32 m0, s38
	ds_read_b128 v[218:221], v169 offset:39936
	global_load_lds_dwordx4 v144, s[28:29]
	s_waitcnt vmcnt(8)
	s_waitcnt lgkmcnt(0)
	s_barrier
	s_setprio 1
	v_mfma_f32_16x16x32_bf16 v[132:135], v[56:59], v[186:189], v[132:135]
	v_mfma_f32_16x16x32_bf16 v[128:131], v[136:139], v[186:189], v[128:131]
	v_mfma_f32_16x16x32_bf16 v[116:119], v[56:59], v[198:201], v[116:119]
	v_mfma_f32_16x16x32_bf16 v[112:115], v[136:139], v[198:201], v[112:115]
	v_mfma_f32_16x16x32_bf16 v[100:103], v[56:59], v[206:209], v[100:103]
	v_mfma_f32_16x16x32_bf16 v[96:99], v[136:139], v[206:209], v[96:99]
	v_mfma_f32_16x16x32_bf16 v[84:87], v[56:59], v[214:217], v[84:87]
	v_mfma_f32_16x16x32_bf16 v[80:83], v[136:139], v[214:217], v[80:83]
	v_mfma_f32_16x16x32_bf16 v[132:135], v[60:63], v[194:197], v[132:135]
	v_mfma_f32_16x16x32_bf16 v[128:131], v[158:161], v[194:197], v[128:131]
	v_mfma_f32_16x16x32_bf16 v[116:119], v[60:63], v[202:205], v[116:119]
	v_mfma_f32_16x16x32_bf16 v[112:115], v[158:161], v[202:205], v[112:115]
	v_mfma_f32_16x16x32_bf16 v[100:103], v[60:63], v[210:213], v[100:103]
	v_mfma_f32_16x16x32_bf16 v[96:99], v[158:161], v[210:213], v[96:99]
	v_mfma_f32_16x16x32_bf16 v[84:87], v[60:63], v[218:221], v[84:87]
	v_mfma_f32_16x16x32_bf16 v[80:83], v[158:161], v[218:221], v[80:83]
	s_setprio 0
	s_setprio 1
	v_mfma_f32_16x16x32_bf16 v[124:127], v[170:173], v[186:189], v[124:127]
	v_mfma_f32_16x16x32_bf16 v[120:123], v[178:181], v[186:189], v[120:123]
	v_mfma_f32_16x16x32_bf16 v[108:111], v[170:173], v[198:201], v[108:111]
	v_mfma_f32_16x16x32_bf16 v[104:107], v[178:181], v[198:201], v[104:107]
	v_mfma_f32_16x16x32_bf16 v[92:95], v[170:173], v[206:209], v[92:95]
	v_mfma_f32_16x16x32_bf16 v[88:91], v[178:181], v[206:209], v[88:91]
	v_mfma_f32_16x16x32_bf16 v[76:79], v[170:173], v[214:217], v[76:79]
	v_mfma_f32_16x16x32_bf16 v[72:75], v[178:181], v[214:217], v[72:75]
	v_mfma_f32_16x16x32_bf16 v[124:127], v[174:177], v[194:197], v[124:127]
	v_mfma_f32_16x16x32_bf16 v[120:123], v[182:185], v[194:197], v[120:123]
	v_mfma_f32_16x16x32_bf16 v[108:111], v[174:177], v[202:205], v[108:111]
	v_mfma_f32_16x16x32_bf16 v[104:107], v[182:185], v[202:205], v[104:107]
	v_mfma_f32_16x16x32_bf16 v[92:95], v[174:177], v[210:213], v[92:95]
	v_mfma_f32_16x16x32_bf16 v[88:91], v[182:185], v[210:213], v[88:91]
	v_mfma_f32_16x16x32_bf16 v[76:79], v[174:177], v[218:221], v[76:79]
	v_mfma_f32_16x16x32_bf16 v[72:75], v[182:185], v[218:221], v[72:75]
	s_setprio 0
	s_barrier
	s_add_i32 s28, s51, s58
	s_mov_b32 m0, s28
	ds_read_b128 v[186:189], v169 offset:49152
	ds_read_b128 v[194:197], v169 offset:50176
	ds_read_b128 v[198:201], v169 offset:51200
	ds_read_b128 v[202:205], v169 offset:52224
	global_load_lds_dwordx4 v142, vcc
	s_add_i32 m0, s28, 0x2000
	s_add_u32 s26, s26, 0x40080
	s_addc_u32 s27, s27, 0
	s_add_i32 s28, s76, s58
	global_load_lds_dwordx4 v146, vcc
	s_mov_b32 m0, s28
	ds_read_b128 v[218:221], v169 offset:56320
	global_load_lds_dwordx4 v142, s[26:27]
	s_add_i32 m0, s28, 0x2000
	ds_read_b128 v[214:217], v169 offset:55296
	global_load_lds_dwordx4 v146, s[26:27]
	s_mov_b32 m0, s42
	ds_read_b128 v[210:213], v169 offset:54272
	global_load_lds_dwordx4 v140, s[100:101]
	s_mov_b32 m0, s59
	ds_read_b128 v[206:209], v169 offset:53248
	global_load_lds_dwordx4 v144, s[100:101]
	s_waitcnt vmcnt(8)
	s_waitcnt lgkmcnt(0)
	s_barrier
	s_setprio 1
	v_mfma_f32_16x16x32_bf16 v[68:71], v[56:59], v[186:189], v[68:71]
	v_mfma_f32_16x16x32_bf16 v[64:67], v[136:139], v[186:189], v[64:67]
	v_mfma_f32_16x16x32_bf16 v[44:47], v[56:59], v[198:201], v[44:47]
	v_mfma_f32_16x16x32_bf16 v[40:43], v[136:139], v[198:201], v[40:43]
	v_mfma_f32_16x16x32_bf16 v[28:31], v[56:59], v[206:209], v[28:31]
	v_mfma_f32_16x16x32_bf16 v[24:27], v[136:139], v[206:209], v[24:27]
	v_mfma_f32_16x16x32_bf16 v[12:15], v[56:59], v[214:217], v[12:15]
	v_mfma_f32_16x16x32_bf16 v[8:11], v[136:139], v[214:217], v[8:11]
	v_mfma_f32_16x16x32_bf16 v[68:71], v[60:63], v[194:197], v[68:71]
	v_mfma_f32_16x16x32_bf16 v[64:67], v[158:161], v[194:197], v[64:67]
	v_mfma_f32_16x16x32_bf16 v[44:47], v[60:63], v[202:205], v[44:47]
	v_mfma_f32_16x16x32_bf16 v[40:43], v[158:161], v[202:205], v[40:43]
	v_mfma_f32_16x16x32_bf16 v[28:31], v[60:63], v[210:213], v[28:31]
	v_mfma_f32_16x16x32_bf16 v[24:27], v[158:161], v[210:213], v[24:27]
	v_mfma_f32_16x16x32_bf16 v[12:15], v[60:63], v[218:221], v[12:15]
	v_mfma_f32_16x16x32_bf16 v[8:11], v[158:161], v[218:221], v[8:11]
	s_setprio 0
	s_setprio 1
	v_mfma_f32_16x16x32_bf16 v[52:55], v[170:173], v[186:189], v[52:55]
	v_mfma_f32_16x16x32_bf16 v[48:51], v[178:181], v[186:189], v[48:51]
	v_mfma_f32_16x16x32_bf16 v[36:39], v[170:173], v[198:201], v[36:39]
	v_mfma_f32_16x16x32_bf16 v[32:35], v[178:181], v[198:201], v[32:35]
	v_mfma_f32_16x16x32_bf16 v[20:23], v[170:173], v[206:209], v[20:23]
	v_mfma_f32_16x16x32_bf16 v[16:19], v[178:181], v[206:209], v[16:19]
	v_mfma_f32_16x16x32_bf16 v[4:7], v[170:173], v[214:217], v[4:7]
	v_mfma_f32_16x16x32_bf16 v[0:3], v[178:181], v[214:217], v[0:3]
	v_mfma_f32_16x16x32_bf16 v[52:55], v[174:177], v[194:197], v[52:55]
	v_mfma_f32_16x16x32_bf16 v[48:51], v[182:185], v[194:197], v[48:51]
	v_mfma_f32_16x16x32_bf16 v[36:39], v[174:177], v[202:205], v[36:39]
	v_mfma_f32_16x16x32_bf16 v[32:35], v[182:185], v[202:205], v[32:35]
	v_mfma_f32_16x16x32_bf16 v[20:23], v[174:177], v[210:213], v[20:23]
	v_mfma_f32_16x16x32_bf16 v[16:19], v[182:185], v[210:213], v[16:19]
	v_mfma_f32_16x16x32_bf16 v[4:7], v[174:177], v[218:221], v[4:7]
	v_mfma_f32_16x16x32_bf16 v[0:3], v[182:185], v[218:221], v[0:3]
	s_setprio 0
	s_barrier
	s_add_i32 s50, s50, 2
	s_add_u32 s24, s24, 0x100
	s_addc_u32 s25, s25, 0
	s_add_u32 s36, s36, 0x100
	s_addc_u32 s37, s37, 0
	s_cmp_gt_u32 s50, 13
	s_cbranch_scc0 .LBB0_119
	s_and_b64 vcc, exec, s[12:13]
	s_cbranch_vccz .LBB0_122
	s_barrier

; #define PG8_STAGE(bufoff, gbase, voff) do { _Pragma("unroll") for (int _i = 0; _i < 2; ++_i) \
;         __builtin_amdgcn_global_load_lds((const unsigned*)((const char*)(gbase) + (voff)[_i]), (PG8_LAS unsigned*)(lds + (bufoff) + ldsw + _i * 8192), 16, 0, 0); } while (0)
; #define PG8_LDA(dst, b, h) do { _Pragma("unroll") for (int m = 0; m < 4; ++m) _Pragma("unroll") for (int k = 0; k < 2; ++k) dst[m][k] = *(const PG8_LAS bf16x8*)(lds + PG8_SA(b, h) + aoff + m * 2048 + k * 1024); } while (0)
; #define PG8_LDB(dst, b, h) do { _Pragma("unroll") for (int n = 0; n < 2; ++n) _Pragma("unroll") for (int k = 0; k < 2; ++k) dst[n][k] = *(const PG8_LAS bf16x8*)(lds + PG8_SB(b, h) + boff + n * 2048 + k * 1024); } while (0)
; #define PG8_WAIT_V(n) asm volatile("s_waitcnt vmcnt(" #n ")" ::: "memory")
; #define PG8_WAIT_L(n) asm volatile("s_waitcnt lgkmcnt(" #n ")" ::: "memory")
; #define PG8_BAR __builtin_amdgcn_s_barrier()
; #define PG8_SCHED __builtin_amdgcn_sched_barrier(0)
; template <class Epi, class Sched, bool ALIGN_EPI = false, bool SP2 = false>
; __device__ __forceinline__ void gemm_phase(PG8_LAS unsigned char* lds, const Gemm g, const Sched& S, const Epi& E) {
;     ...
;         const bool has_next = S.next(ui + 1, nxt);
;         const char* nA = has_next ? (const char*)g.A + (size_t)nxt.pm * tstep + (size_t)nxt.pn * g.a_pn_off : cA; const char* nB = has_next ? (const char*)g.Bt + (size_t)nxt.pn * tstep : cB;
;         for (int t = 0; t < nt; t += 2) {
;             const bool last = (t == nt - 2);
;             const char* a1 = cA + (size_t)(t + 1) * kstep;
;             const char* a2 = last ? nA : cA + (size_t)(t + 2) * kstep; const char* b2 = last ? nB : cB + (size_t)(t + 2) * kstep;
;             const char* a3 = a2 + kstep; const char* b3 = b2 + kstep;
;             if (last && has_next) S.a_ready(nxt);
;             if constexpr (SP2) {
;             PG8_LDB(B0, 0, 0); PG8_LDB(B1, 0, 1); PG8_SCHED; PG8_LDA(At, 0, 0); PG8_STAGE(PG8_SA(1, 1), a1 + hstep, voffA);
;             PG8_WAIT_V(8); PG8_WAIT_L(0); PG8_BAR; PG8_MMA(0, 0, At, B0); PG8_MMA(0, 1, At, B1); PG8_BAR; PG8_SCHED;
;             PG8_LDA(At, 0, 1); PG8_STAGE(PG8_SB(0, 0), b2, voffB); PG8_STAGE(PG8_SB(0, 1), b2 + hstep, voffB); PG8_STAGE(PG8_SA(0, 0), a2, voffA);
;             PG8_WAIT_V(8); PG8_WAIT_L(0); PG8_BAR; PG8_MMA(1, 0, At, B0); PG8_MMA(1, 1, At, B1); PG8_BAR; PG8_SCHED;
.LBB0_379:
	s_ashr_i32 s17, s16, 31
	s_lshl_b64 s[18:19], s[16:17], 16
	s_add_u32 s17, s84, s18
	s_addc_u32 s20, s85, s19
	s_ashr_i32 s15, s14, 31
	s_lshl_b64 s[18:19], s[14:15], 24
	s_add_u32 s18, s17, s18
	s_addc_u32 s19, s20, s19
	s_and_b64 s[20:21], s[2:3], exec
	s_cselect_b32 s29, s19, s27
	s_cselect_b32 s28, s18, s26
	s_lshl_b64 s[20:21], s[14:15], 16
	s_add_u32 s20, s58, s20
	s_addc_u32 s21, s59, s21
	s_add_u32 s40, s26, 0x8080
	ds_read_b128 v[0:3], v163
	ds_read_b128 v[4:7], v163 offset:1024
	ds_read_b128 v[8:11], v163 offset:2048
	ds_read_b128 v[12:15], v163 offset:3072
	ds_read_b128 v[16:19], v164
	ds_read_b128 v[20:23], v164 offset:1024
	ds_read_b128 v[24:27], v164 offset:2048
	ds_read_b128 v[28:31], v164 offset:3072
	s_addc_u32 s41, s27, 0
	s_add_u32 s26, s28, 0x8000
	s_addc_u32 s27, s29, 0
	s_and_b64 s[50:51], s[2:3], exec
	s_cselect_b32 s24, s20, s24
	s_cselect_b32 s25, s21, s25
	s_add_u32 s50, s24, 0x8000
	s_addc_u32 s51, s25, 0
	v_lshl_add_u64 v[64:65], s[40:41], 0, v[150:151]
	s_add_i32 m0, s1, 0xc000
	ds_read_b128 v[32:35], v165
	ds_read_b128 v[36:39], v165 offset:1024
	ds_read_b128 v[40:43], v165 offset:2048
	ds_read_b128 v[44:47], v165 offset:3072
	ds_read_b128 v[48:51], v165 offset:4096
	ds_read_b128 v[52:55], v165 offset:5120
	ds_read_b128 v[56:59], v165 offset:6144
	ds_read_b128 v[60:63], v165 offset:7168
	global_load_lds_dwordx4 v[64:65], off
	v_lshl_add_u64 v[64:65], s[40:41], 0, v[146:147]
	s_add_i32 m0, s1, 0xe000
	s_nop 0
	global_load_lds_dwordx4 v[64:65], off
	s_waitcnt vmcnt(8)
	s_waitcnt lgkmcnt(0)
	s_barrier
	s_setprio 1
	v_mfma_f32_16x16x32_bf16 v[64:67], v[0:3], v[32:35], 0
	v_mfma_f32_16x16x32_bf16 v[68:71], v[8:11], v[32:35], 0
	v_mfma_f32_16x16x32_bf16 v[72:75], v[0:3], v[40:43], 0
	v_mfma_f32_16x16x32_bf16 v[76:79], v[8:11], v[40:43], 0
	v_mfma_f32_16x16x32_bf16 v[80:83], v[0:3], v[48:51], 0
	v_mfma_f32_16x16x32_bf16 v[84:87], v[8:11], v[48:51], 0
	v_mfma_f32_16x16x32_bf16 v[88:91], v[0:3], v[56:59], 0
	v_mfma_f32_16x16x32_bf16 v[92:95], v[8:11], v[56:59], 0
	v_mfma_f32_16x16x32_bf16 v[64:67], v[4:7], v[36:39], v[64:67]
	v_mfma_f32_16x16x32_bf16 v[68:71], v[12:15], v[36:39], v[68:71]
	v_mfma_f32_16x16x32_bf16 v[72:75], v[4:7], v[44:47], v[72:75]
	v_mfma_f32_16x16x32_bf16 v[76:79], v[12:15], v[44:47], v[76:79]
	v_mfma_f32_16x16x32_bf16 v[80:83], v[4:7], v[52:55], v[80:83]
	v_mfma_f32_16x16x32_bf16 v[84:87], v[12:15], v[52:55], v[84:87]
	v_mfma_f32_16x16x32_bf16 v[88:91], v[4:7], v[60:63], v[88:91]
	v_mfma_f32_16x16x32_bf16 v[96:99], v[12:15], v[60:63], v[92:95]
	s_setprio 0
	s_setprio 1
	v_mfma_f32_16x16x32_bf16 v[92:95], v[16:19], v[32:35], 0
	v_mfma_f32_16x16x32_bf16 v[32:35], v[24:27], v[32:35], 0
	v_mfma_f32_16x16x32_bf16 v[100:103], v[20:23], v[36:39], v[92:95]
	v_mfma_f32_16x16x32_bf16 v[32:35], v[28:31], v[36:39], v[32:35]
	v_mfma_f32_16x16x32_bf16 v[36:39], v[16:19], v[40:43], 0
	v_mfma_f32_16x16x32_bf16 v[40:43], v[24:27], v[40:43], 0
	v_mfma_f32_16x16x32_bf16 v[36:39], v[20:23], v[44:47], v[36:39]
	v_mfma_f32_16x16x32_bf16 v[40:43], v[28:31], v[44:47], v[40:43]
	v_mfma_f32_16x16x32_bf16 v[44:47], v[16:19], v[48:51], 0
	v_mfma_f32_16x16x32_bf16 v[48:51], v[24:27], v[48:51], 0
	v_mfma_f32_16x16x32_bf16 v[44:47], v[20:23], v[52:55], v[44:47]
	v_mfma_f32_16x16x32_bf16 v[48:51], v[28:31], v[52:55], v[48:51]
	v_mfma_f32_16x16x32_bf16 v[52:55], v[16:19], v[56:59], 0
	v_mfma_f32_16x16x32_bf16 v[56:59], v[24:27], v[56:59], 0
	v_mfma_f32_16x16x32_bf16 v[52:55], v[20:23], v[60:63], v[52:55]
	v_mfma_f32_16x16x32_bf16 v[56:59], v[28:31], v[60:63], v[56:59]
	s_setprio 0
	s_barrier
	s_add_i32 s15, s37, s0
	v_lshl_add_u64 v[250:251], s[24:25], 0, v[148:149]
	s_mov_b32 m0, s15
	ds_read_b128 v[60:63], v165 offset:16384
	ds_read_b128 v[92:95], v165 offset:17408
	ds_read_b128 v[104:107], v165 offset:18432
	ds_read_b128 v[108:111], v165 offset:19456
	ds_read_b128 v[112:115], v165 offset:20480
	ds_read_b128 v[116:119], v165 offset:21504
	ds_read_b128 v[120:123], v165 offset:22528
	ds_read_b128 v[124:127], v165 offset:23552
	global_load_lds_dwordx4 v[250:251], off
	v_lshl_add_u64 v[252:253], s[24:25], 0, v[144:145]
	s_add_i32 m0, s15, 0x2000
	s_add_i32 s15, s38, s0
	global_load_lds_dwordx4 v[252:253], off
	v_lshl_add_u64 v[128:129], s[50:51], 0, v[148:149]
	s_mov_b32 m0, s15
	v_lshl_add_u64 v[192:193], s[28:29], 0, v[150:151]
	global_load_lds_dwordx4 v[128:129], off
	v_lshl_add_u64 v[128:129], s[50:51], 0, v[144:145]
	s_add_i32 m0, s15, 0x2000
	v_lshl_add_u64 v[152:153], s[28:29], 0, v[146:147]
	global_load_lds_dwordx4 v[128:129], off
	s_mov_b32 m0, s1
	s_nop 0
	global_load_lds_dwordx4 v[192:193], off
	s_mov_b32 m0, s23
	s_nop 0
	global_load_lds_dwordx4 v[152:153], off
	s_waitcnt vmcnt(8)
	s_waitcnt lgkmcnt(0)
	s_barrier
; #define PG8_STAGE(bufoff, gbase, voff) do { _Pragma("unroll") for (int _i = 0; _i < 2; ++_i) \
;         __builtin_amdgcn_global_load_lds((const unsigned*)((const char*)(gbase) + (voff)[_i]), (PG8_LAS unsigned*)(lds + (bufoff) + ldsw + _i * 8192), 16, 0, 0); } while (0)
; #define PG8_LDA(dst, b, h) do { _Pragma("unroll") for (int m = 0; m < 4; ++m) _Pragma("unroll") for (int k = 0; k < 2; ++k) dst[m][k] = *(const PG8_LAS bf16x8*)(lds + PG8_SA(b, h) + aoff + m * 2048 + k * 1024); } while (0)
; #define PG8_LDB(dst, b, h) do { _Pragma("unroll") for (int n = 0; n < 2; ++n) _Pragma("unroll") for (int k = 0; k < 2; ++k) dst[n][k] = *(const PG8_LAS bf16x8*)(lds + PG8_SB(b, h) + boff + n * 2048 + k * 1024); } while (0)
; #define PG8_MMA(ai, bj, At, Bt) do { __builtin_amdgcn_s_setprio(1); _Pragma("unroll") for (int m = 0; m < 4; ++m) _Pragma("unroll") for (int n = 0; n < 2; ++n) _Pragma("unroll") for (int k = 0; k < 2; ++k) \
;         acc[ai][bj][m][n] = __builtin_amdgcn_mfma_f32_16x16x32_bf16(Bt[n][k], At[m][k], acc[ai][bj][m][n], 0, 0, 0); __builtin_amdgcn_s_setprio(0); } while (0)
; #define PG8_WAIT_V(n) asm volatile("s_waitcnt vmcnt(" #n ")" ::: "memory")
; #define PG8_WAIT_L(n) asm volatile("s_waitcnt lgkmcnt(" #n ")" ::: "memory")
; #define PG8_BAR __builtin_amdgcn_s_barrier()
; #define PG8_SCHED __builtin_amdgcn_sched_barrier(0)
; template <class Epi, class Sched, bool ALIGN_EPI = false, bool SP2 = false>
; __device__ __forceinline__ void gemm_phase(PG8_LAS unsigned char* lds, const Gemm g, const Sched& S, const Epi& E) {
;     ...
;             PG8_WAIT_V(8); PG8_WAIT_L(0); PG8_BAR; PG8_MMA(1, 0, At, B0); PG8_MMA(1, 1, At, B1); PG8_BAR; PG8_SCHED;
;             PG8_LDB(B0, 1, 0); PG8_LDB(B1, 1, 1); PG8_SCHED; PG8_LDA(At, 1, 0); PG8_STAGE(PG8_SA(0, 1), a2 + hstep, voffA);
;             PG8_WAIT_V(8); PG8_WAIT_L(0); PG8_BAR; PG8_MMA(0, 0, At, B0); PG8_MMA(0, 1, At, B1); PG8_BAR; PG8_SCHED;
	s_setprio 1
	v_mfma_f32_16x16x32_bf16 v[128:131], v[0:3], v[60:63], 0
	v_mfma_f32_16x16x32_bf16 v[156:159], v[4:7], v[92:95], v[128:131]
	v_mfma_f32_16x16x32_bf16 v[128:131], v[8:11], v[60:63], 0
	v_mfma_f32_16x16x32_bf16 v[166:169], v[12:15], v[92:95], v[128:131]
	v_mfma_f32_16x16x32_bf16 v[128:131], v[0:3], v[104:107], 0
	v_mfma_f32_16x16x32_bf16 v[170:173], v[4:7], v[108:111], v[128:131]
	v_mfma_f32_16x16x32_bf16 v[128:131], v[8:11], v[104:107], 0
	v_mfma_f32_16x16x32_bf16 v[174:177], v[12:15], v[108:111], v[128:131]
	v_mfma_f32_16x16x32_bf16 v[128:131], v[0:3], v[112:115], 0
	v_mfma_f32_16x16x32_bf16 v[0:3], v[0:3], v[120:123], 0
	v_mfma_f32_16x16x32_bf16 v[178:181], v[4:7], v[116:119], v[128:131]
	v_mfma_f32_16x16x32_bf16 v[0:3], v[4:7], v[124:127], v[0:3]
	v_mfma_f32_16x16x32_bf16 v[4:7], v[8:11], v[120:123], 0
	v_mfma_f32_16x16x32_bf16 v[128:131], v[8:11], v[112:115], 0
	v_mfma_f32_16x16x32_bf16 v[4:7], v[12:15], v[124:127], v[4:7]
	v_mfma_f32_16x16x32_bf16 v[182:185], v[12:15], v[116:119], v[128:131]
	s_setprio 0
	s_setprio 1
	v_mfma_f32_16x16x32_bf16 v[8:11], v[16:19], v[60:63], 0
	v_mfma_f32_16x16x32_bf16 v[12:15], v[24:27], v[60:63], 0
	v_mfma_f32_16x16x32_bf16 v[60:63], v[16:19], v[104:107], 0
	v_mfma_f32_16x16x32_bf16 v[186:189], v[20:23], v[108:111], v[60:63]
	v_mfma_f32_16x16x32_bf16 v[60:63], v[24:27], v[104:107], 0
	v_mfma_f32_16x16x32_bf16 v[194:197], v[28:31], v[108:111], v[60:63]
	v_mfma_f32_16x16x32_bf16 v[60:63], v[16:19], v[112:115], 0
	v_mfma_f32_16x16x32_bf16 v[16:19], v[16:19], v[120:123], 0
	v_mfma_f32_16x16x32_bf16 v[198:201], v[20:23], v[116:119], v[60:63]
	v_mfma_f32_16x16x32_bf16 v[60:63], v[24:27], v[112:115], 0
	v_mfma_f32_16x16x32_bf16 v[206:209], v[20:23], v[124:127], v[16:19]
	v_mfma_f32_16x16x32_bf16 v[16:19], v[24:27], v[120:123], 0
	v_mfma_f32_16x16x32_bf16 v[8:11], v[20:23], v[92:95], v[8:11]
	v_mfma_f32_16x16x32_bf16 v[12:15], v[28:31], v[92:95], v[12:15]
	v_mfma_f32_16x16x32_bf16 v[202:205], v[28:31], v[116:119], v[60:63]
	v_mfma_f32_16x16x32_bf16 v[24:27], v[28:31], v[124:127], v[16:19]
	s_setprio 0
	s_barrier
	s_add_i32 s15, 0, 0x18000
	v_add_u32_e32 v60, s15, v161
	s_add_i32 s17, 0, 0x1c000
	ds_read_b128 v[16:19], v60
	ds_read_b128 v[20:23], v60 offset:1024
	ds_read_b128 v[28:31], v60 offset:2048
	ds_read_b128 v[210:213], v60 offset:3072
	v_add_u32_e32 v60, s17, v161
	ds_read_b128 v[214:217], v60
	ds_read_b128 v[218:221], v60 offset:1024
	ds_read_b128 v[222:225], v60 offset:2048
	ds_read_b128 v[226:229], v60 offset:3072
	s_mov_b32 m0, s31
	v_lshl_add_u64 v[92:93], s[26:27], 0, v[150:151]
	ds_read_b128 v[60:63], v165 offset:32768
	ds_read_b128 v[112:115], v165 offset:33792
	ds_read_b128 v[116:119], v165 offset:34816
	ds_read_b128 v[230:233], v165 offset:35840
	ds_read_b128 v[234:237], v165 offset:36864
	ds_read_b128 v[238:241], v165 offset:37888
	ds_read_b128 v[242:245], v165 offset:38912
	ds_read_b128 v[246:249], v165 offset:39936
	global_load_lds_dwordx4 v[92:93], off
	v_lshl_add_u64 v[92:93], s[26:27], 0, v[146:147]
	s_mov_b32 m0, s34
	s_nop 0
	global_load_lds_dwordx4 v[92:93], off
	s_waitcnt vmcnt(8)
	s_waitcnt lgkmcnt(0)
	s_barrier
	s_setprio 1
	v_mfma_f32_16x16x32_bf16 v[64:67], v[16:19], v[60:63], v[64:67]
	v_mfma_f32_16x16x32_bf16 v[140:143], v[20:23], v[112:115], v[64:67]
	v_mfma_f32_16x16x32_bf16 v[64:67], v[28:31], v[60:63], v[68:71]
	v_mfma_f32_16x16x32_bf16 v[136:139], v[210:213], v[112:115], v[64:67]
	v_mfma_f32_16x16x32_bf16 v[64:67], v[16:19], v[116:119], v[72:75]
	v_mfma_f32_16x16x32_bf16 v[124:127], v[20:23], v[230:233], v[64:67]
	v_mfma_f32_16x16x32_bf16 v[64:67], v[28:31], v[116:119], v[76:79]
	v_mfma_f32_16x16x32_bf16 v[120:123], v[210:213], v[230:233], v[64:67]
	v_mfma_f32_16x16x32_bf16 v[64:67], v[16:19], v[234:237], v[80:83]
	v_mfma_f32_16x16x32_bf16 v[108:111], v[20:23], v[238:241], v[64:67]
	v_mfma_f32_16x16x32_bf16 v[64:67], v[28:31], v[234:237], v[84:87]
	v_mfma_f32_16x16x32_bf16 v[104:107], v[210:213], v[238:241], v[64:67]
	v_mfma_f32_16x16x32_bf16 v[64:67], v[16:19], v[242:245], v[88:91]
	v_mfma_f32_16x16x32_bf16 v[92:95], v[20:23], v[246:249], v[64:67]
	v_mfma_f32_16x16x32_bf16 v[64:67], v[28:31], v[242:245], v[96:99]
	v_mfma_f32_16x16x32_bf16 v[88:91], v[210:213], v[246:249], v[64:67]
	s_setprio 0
	s_setprio 1
	v_mfma_f32_16x16x32_bf16 v[32:35], v[222:225], v[60:63], v[32:35]
	v_mfma_f32_16x16x32_bf16 v[64:67], v[214:217], v[60:63], v[100:103]
	v_mfma_f32_16x16x32_bf16 v[132:135], v[226:229], v[112:115], v[32:35]
	v_mfma_f32_16x16x32_bf16 v[32:35], v[214:217], v[116:119], v[36:39]
	v_mfma_f32_16x16x32_bf16 v[128:131], v[218:221], v[112:115], v[64:67]
	v_mfma_f32_16x16x32_bf16 v[112:115], v[218:221], v[230:233], v[32:35]
	v_mfma_f32_16x16x32_bf16 v[32:35], v[222:225], v[116:119], v[40:43]
	v_mfma_f32_16x16x32_bf16 v[116:119], v[226:229], v[230:233], v[32:35]
	v_mfma_f32_16x16x32_bf16 v[32:35], v[214:217], v[234:237], v[44:47]
	v_mfma_f32_16x16x32_bf16 v[96:99], v[218:221], v[238:241], v[32:35]
	v_mfma_f32_16x16x32_bf16 v[32:35], v[222:225], v[234:237], v[48:51]
	v_mfma_f32_16x16x32_bf16 v[100:103], v[226:229], v[238:241], v[32:35]
	v_mfma_f32_16x16x32_bf16 v[32:35], v[214:217], v[242:245], v[52:55]
	v_mfma_f32_16x16x32_bf16 v[80:83], v[218:221], v[246:249], v[32:35]
	v_mfma_f32_16x16x32_bf16 v[32:35], v[222:225], v[242:245], v[56:59]
	v_mfma_f32_16x16x32_bf16 v[84:87], v[226:229], v[246:249], v[32:35]
	s_setprio 0
	s_barrier
; #define PG8_STAGE(bufoff, gbase, voff) do { _Pragma("unroll") for (int _i = 0; _i < 2; ++_i) \
;         __builtin_amdgcn_global_load_lds((const unsigned*)((const char*)(gbase) + (voff)[_i]), (PG8_LAS unsigned*)(lds + (bufoff) + ldsw + _i * 8192), 16, 0, 0); } while (0)
; #define PG8_LDA(dst, b, h) do { _Pragma("unroll") for (int m = 0; m < 4; ++m) _Pragma("unroll") for (int k = 0; k < 2; ++k) dst[m][k] = *(const PG8_LAS bf16x8*)(lds + PG8_SA(b, h) + aoff + m * 2048 + k * 1024); } while (0)
; #define PG8_MMA(ai, bj, At, Bt) do { __builtin_amdgcn_s_setprio(1); _Pragma("unroll") for (int m = 0; m < 4; ++m) _Pragma("unroll") for (int n = 0; n < 2; ++n) _Pragma("unroll") for (int k = 0; k < 2; ++k) \
;         acc[ai][bj][m][n] = __builtin_amdgcn_mfma_f32_16x16x32_bf16(Bt[n][k], At[m][k], acc[ai][bj][m][n], 0, 0, 0); __builtin_amdgcn_s_setprio(0); } while (0)
; #define PG8_WAIT_V(n) asm volatile("s_waitcnt vmcnt(" #n ")" ::: "memory")
; #define PG8_WAIT_L(n) asm volatile("s_waitcnt lgkmcnt(" #n ")" ::: "memory")
; #define PG8_BAR __builtin_amdgcn_s_barrier()
; #define PG8_SCHED __builtin_amdgcn_sched_barrier(0)
; template <class Epi, class Sched, bool ALIGN_EPI = false, bool SP2 = false>
; __device__ __forceinline__ void gemm_phase(PG8_LAS unsigned char* lds, const Gemm g, const Sched& S, const Epi& E) {
;     ...
;             PG8_LDA(At, 1, 1); PG8_STAGE(PG8_SB(1, 0), b3, voffB); PG8_STAGE(PG8_SB(1, 1), b3 + hstep, voffB); PG8_STAGE(PG8_SA(1, 0), a3, voffA);
;             PG8_WAIT_V(8); PG8_WAIT_L(0); PG8_BAR; PG8_MMA(1, 0, At, B0); PG8_MMA(1, 1, At, B1); PG8_BAR; PG8_SCHED;
;     ...
;         if constexpr (ALIGN_EPI) { if (wr == 0) PG8_BAR; }
	s_add_i32 s15, s15, s0
	v_lshl_add_u64 v[40:41], v[250:251], 0, s[6:7]
	s_mov_b32 m0, s15
	s_nop 1
	ds_read_b128 v[32:35], v165 offset:49152
	ds_read_b128 v[36:39], v165 offset:50176
	ds_read_b128 v[52:55], v165 offset:51200
	ds_read_b128 v[230:233], v165 offset:52224
	ds_read_b128 v[234:237], v165 offset:53248
	ds_read_b128 v[238:241], v165 offset:54272
	ds_read_b128 v[242:245], v165 offset:55296
	ds_read_b128 v[246:249], v165 offset:56320
	global_load_lds_dwordx4 v[40:41], off
	s_add_i32 m0, s15, 0x2000
	s_add_u32 s24, s24, 0x8080
	v_lshl_add_u64 v[40:41], v[252:253], 0, s[6:7]
	s_addc_u32 s25, s25, 0
	s_add_i32 s15, s17, s0
	global_load_lds_dwordx4 v[40:41], off
	v_lshl_add_u64 v[40:41], s[24:25], 0, v[148:149]
	s_mov_b32 m0, s15
	s_nop 0
	global_load_lds_dwordx4 v[40:41], off
	v_lshl_add_u64 v[40:41], s[24:25], 0, v[144:145]
	s_add_i32 m0, s15, 0x2000
	s_nop 0
	global_load_lds_dwordx4 v[40:41], off
	v_lshl_add_u64 v[40:41], v[192:193], 0, s[6:7]
	s_mov_b32 m0, s35
	s_nop 0
	global_load_lds_dwordx4 v[40:41], off
	v_lshl_add_u64 v[40:41], v[152:153], 0, s[6:7]
	s_mov_b32 m0, s36
	s_nop 0
	global_load_lds_dwordx4 v[40:41], off
	s_waitcnt vmcnt(8)
	s_waitcnt lgkmcnt(0)
	s_barrier
	s_setprio 1
	v_mfma_f32_16x16x32_bf16 v[40:43], v[16:19], v[32:35], v[156:159]
	v_mfma_f32_16x16x32_bf16 v[76:79], v[20:23], v[36:39], v[40:43]
	v_mfma_f32_16x16x32_bf16 v[40:43], v[28:31], v[32:35], v[166:169]
	v_mfma_f32_16x16x32_bf16 v[72:75], v[210:213], v[36:39], v[40:43]
	v_mfma_f32_16x16x32_bf16 v[40:43], v[16:19], v[52:55], v[170:173]
	v_mfma_f32_16x16x32_bf16 v[60:63], v[20:23], v[230:233], v[40:43]
	v_mfma_f32_16x16x32_bf16 v[40:43], v[28:31], v[52:55], v[174:177]
	v_mfma_f32_16x16x32_bf16 v[56:59], v[210:213], v[230:233], v[40:43]
	v_mfma_f32_16x16x32_bf16 v[40:43], v[16:19], v[234:237], v[178:181]
	v_mfma_f32_16x16x32_bf16 v[0:3], v[16:19], v[242:245], v[0:3]
	v_mfma_f32_16x16x32_bf16 v[44:47], v[20:23], v[238:241], v[40:43]
	v_mfma_f32_16x16x32_bf16 v[40:43], v[28:31], v[234:237], v[182:185]
	v_mfma_f32_16x16x32_bf16 v[20:23], v[20:23], v[246:249], v[0:3]
	v_mfma_f32_16x16x32_bf16 v[0:3], v[28:31], v[242:245], v[4:7]
	v_mfma_f32_16x16x32_bf16 v[40:43], v[210:213], v[238:241], v[40:43]
	v_mfma_f32_16x16x32_bf16 v[16:19], v[210:213], v[246:249], v[0:3]
	s_setprio 0
	s_setprio 1
	v_mfma_f32_16x16x32_bf16 v[0:3], v[214:217], v[32:35], v[8:11]
	v_mfma_f32_16x16x32_bf16 v[64:67], v[218:221], v[36:39], v[0:3]
	v_mfma_f32_16x16x32_bf16 v[0:3], v[222:225], v[32:35], v[12:15]
	v_mfma_f32_16x16x32_bf16 v[68:71], v[226:229], v[36:39], v[0:3]
	v_mfma_f32_16x16x32_bf16 v[0:3], v[214:217], v[52:55], v[186:189]
	v_mfma_f32_16x16x32_bf16 v[48:51], v[218:221], v[230:233], v[0:3]
	v_mfma_f32_16x16x32_bf16 v[0:3], v[222:225], v[52:55], v[194:197]
	v_mfma_f32_16x16x32_bf16 v[52:55], v[226:229], v[230:233], v[0:3]
	v_mfma_f32_16x16x32_bf16 v[0:3], v[214:217], v[234:237], v[198:201]
	v_mfma_f32_16x16x32_bf16 v[32:35], v[218:221], v[238:241], v[0:3]
	v_mfma_f32_16x16x32_bf16 v[0:3], v[222:225], v[234:237], v[202:205]
	v_mfma_f32_16x16x32_bf16 v[36:39], v[226:229], v[238:241], v[0:3]
	v_mfma_f32_16x16x32_bf16 v[0:3], v[214:217], v[242:245], v[206:209]
	v_mfma_f32_16x16x32_bf16 v[4:7], v[218:221], v[246:249], v[0:3]
	v_mfma_f32_16x16x32_bf16 v[0:3], v[222:225], v[242:245], v[24:27]
	v_mfma_f32_16x16x32_bf16 v[0:3], v[226:229], v[246:249], v[0:3]
	s_setprio 0
	s_barrier
	s_andn2_b64 vcc, exec, s[10:11]
	s_cbranch_vccnz .LBB0_381
	s_barrier

; #define PG8_STAGE(bufoff, gbase, voff) do { _Pragma("unroll") for (int _i = 0; _i < 2; ++_i) \
;         __builtin_amdgcn_global_load_lds((const unsigned*)((const char*)(gbase) + (voff)[_i]), (PG8_LAS unsigned*)(lds + (bufoff) + ldsw + _i * 8192), 16, 0, 0); } while (0)
; #define PG8_LDA(dst, b, h) do { _Pragma("unroll") for (int m = 0; m < 4; ++m) _Pragma("unroll") for (int k = 0; k < 2; ++k) dst[m][k] = *(const PG8_LAS bf16x8*)(lds + PG8_SA(b, h) + aoff + m * 2048 + k * 1024); } while (0)
; #define PG8_LDB(dst, b, h) do { _Pragma("unroll") for (int n = 0; n < 2; ++n) _Pragma("unroll") for (int k = 0; k < 2; ++k) dst[n][k] = *(const PG8_LAS bf16x8*)(lds + PG8_SB(b, h) + boff + n * 2048 + k * 1024); } while (0)
; #define PG8_MMA(ai, bj, At, Bt) do { __builtin_amdgcn_s_setprio(1); _Pragma("unroll") for (int m = 0; m < 4; ++m) _Pragma("unroll") for (int n = 0; n < 2; ++n) _Pragma("unroll") for (int k = 0; k < 2; ++k) \
;         acc[ai][bj][m][n] = __builtin_amdgcn_mfma_f32_16x16x32_bf16(Bt[n][k], At[m][k], acc[ai][bj][m][n], 0, 0, 0); __builtin_amdgcn_s_setprio(0); } while (0)
; #define PG8_WAIT_V(n) asm volatile("s_waitcnt vmcnt(" #n ")" ::: "memory")
; #define PG8_WAIT_L(n) asm volatile("s_waitcnt lgkmcnt(" #n ")" ::: "memory")
; #define PG8_BAR __builtin_amdgcn_s_barrier()
; #define PG8_SCHED __builtin_amdgcn_sched_barrier(0)
; template <class Epi, class Sched, bool ALIGN_EPI = false, bool SP2 = false>
; __device__ __forceinline__ void gemm_phase(PG8_LAS unsigned char* lds, const Gemm g, const Sched& S, const Epi& E) {
;     ...
;             PG8_LDB(B0, 0, 0); PG8_LDB(B1, 0, 1); PG8_SCHED; PG8_LDA(At, 0, 0); PG8_STAGE(PG8_SA(1, 1), a1 + hstep, voffA);
;             PG8_WAIT_V(8); PG8_WAIT_L(0); PG8_BAR; PG8_MMA(0, 0, At, B0); PG8_MMA(0, 1, At, B1); PG8_BAR; PG8_SCHED;
;             PG8_LDA(At, 0, 1); PG8_STAGE(PG8_SB(0, 0), b2, voffB); PG8_STAGE(PG8_SB(0, 1), b2 + hstep, voffB); PG8_STAGE(PG8_SA(0, 0), a2, voffA);
;             PG8_WAIT_V(8); PG8_WAIT_L(0); PG8_BAR; PG8_MMA(1, 0, At, B0); PG8_MMA(1, 1, At, B1); PG8_BAR; PG8_SCHED;
.LBB0_413:
	ds_read_b128 v[144:147], v151
	ds_read_b128 v[154:157], v151 offset:1024
	ds_read_b128 v[158:161], v151 offset:2048
	ds_read_b128 v[162:165], v151 offset:3072
	ds_read_b128 v[166:169], v152
	ds_read_b128 v[170:173], v152 offset:1024
	ds_read_b128 v[174:177], v152 offset:2048
	ds_read_b128 v[178:181], v152 offset:3072
	s_add_u32 s36, s34, 0xfffc0080
	s_addc_u32 s37, s35, -1
	s_cmp_eq_u32 s64, 12
	s_cselect_b32 s41, s23, s37
	s_cselect_b32 s40, s29, s36
	s_cselect_b32 s37, s21, s63
	s_cselect_b32 s36, s59, s62
	s_add_u32 vcc_lo, s36, 0x80
	s_addc_u32 vcc_hi, s37, 0
	s_add_u32 s100, s40, 0x80
	s_addc_u32 s101, s41, 0
	s_add_i32 m0, s1, 0xc000
	ds_read_b128 v[182:185], v153
	ds_read_b128 v[186:189], v153 offset:1024
	ds_read_b128 v[194:197], v153 offset:2048
	ds_read_b128 v[198:201], v153 offset:3072
	ds_read_b128 v[202:205], v153 offset:4096
	ds_read_b128 v[206:209], v153 offset:5120
	ds_read_b128 v[210:213], v153 offset:6144
	global_load_lds_dwordx4 v136, s[34:35]
	s_add_i32 m0, s1, 0xe000
	ds_read_b128 v[214:217], v153 offset:7168
	global_load_lds_dwordx4 v138, s[34:35]
	s_waitcnt vmcnt(8)
	s_waitcnt lgkmcnt(0)
	s_barrier
	s_setprio 1
	v_mfma_f32_16x16x32_bf16 v[124:127], v[144:147], v[182:185], v[124:127]
	v_mfma_f32_16x16x32_bf16 v[120:123], v[158:161], v[182:185], v[120:123]
	v_mfma_f32_16x16x32_bf16 v[108:111], v[144:147], v[194:197], v[108:111]
	v_mfma_f32_16x16x32_bf16 v[104:107], v[158:161], v[194:197], v[104:107]
	v_mfma_f32_16x16x32_bf16 v[92:95], v[144:147], v[202:205], v[92:95]
	v_mfma_f32_16x16x32_bf16 v[88:91], v[158:161], v[202:205], v[88:91]
	v_mfma_f32_16x16x32_bf16 v[76:79], v[144:147], v[210:213], v[76:79]
	v_mfma_f32_16x16x32_bf16 v[72:75], v[158:161], v[210:213], v[72:75]
	v_mfma_f32_16x16x32_bf16 v[124:127], v[154:157], v[186:189], v[124:127]
	v_mfma_f32_16x16x32_bf16 v[120:123], v[162:165], v[186:189], v[120:123]
	v_mfma_f32_16x16x32_bf16 v[108:111], v[154:157], v[198:201], v[108:111]
	v_mfma_f32_16x16x32_bf16 v[104:107], v[162:165], v[198:201], v[104:107]
	v_mfma_f32_16x16x32_bf16 v[92:95], v[154:157], v[206:209], v[92:95]
	v_mfma_f32_16x16x32_bf16 v[88:91], v[162:165], v[206:209], v[88:91]
	v_mfma_f32_16x16x32_bf16 v[76:79], v[154:157], v[214:217], v[76:79]
	v_mfma_f32_16x16x32_bf16 v[72:75], v[162:165], v[214:217], v[72:75]
	s_setprio 0
	s_setprio 1
	v_mfma_f32_16x16x32_bf16 v[116:119], v[166:169], v[182:185], v[116:119]
	v_mfma_f32_16x16x32_bf16 v[112:115], v[174:177], v[182:185], v[112:115]
	v_mfma_f32_16x16x32_bf16 v[100:103], v[166:169], v[194:197], v[100:103]
	v_mfma_f32_16x16x32_bf16 v[96:99], v[174:177], v[194:197], v[96:99]
	v_mfma_f32_16x16x32_bf16 v[84:87], v[166:169], v[202:205], v[84:87]
	v_mfma_f32_16x16x32_bf16 v[80:83], v[174:177], v[202:205], v[80:83]
	v_mfma_f32_16x16x32_bf16 v[68:71], v[166:169], v[210:213], v[68:71]
	v_mfma_f32_16x16x32_bf16 v[64:67], v[174:177], v[210:213], v[64:67]
	v_mfma_f32_16x16x32_bf16 v[116:119], v[170:173], v[186:189], v[116:119]
	v_mfma_f32_16x16x32_bf16 v[112:115], v[178:181], v[186:189], v[112:115]
	v_mfma_f32_16x16x32_bf16 v[100:103], v[170:173], v[198:201], v[100:103]
	v_mfma_f32_16x16x32_bf16 v[96:99], v[178:181], v[198:201], v[96:99]
	v_mfma_f32_16x16x32_bf16 v[84:87], v[170:173], v[206:209], v[84:87]
	v_mfma_f32_16x16x32_bf16 v[80:83], v[178:181], v[206:209], v[80:83]
	v_mfma_f32_16x16x32_bf16 v[68:71], v[170:173], v[214:217], v[68:71]
	v_mfma_f32_16x16x32_bf16 v[64:67], v[178:181], v[214:217], v[64:67]
	s_setprio 0
	s_barrier
	s_add_i32 s65, s50, s0
	s_mov_b32 m0, s65
	ds_read_b128 v[182:185], v153 offset:16384
	ds_read_b128 v[186:189], v153 offset:17408
	ds_read_b128 v[194:197], v153 offset:18432
	ds_read_b128 v[198:201], v153 offset:19456
	global_load_lds_dwordx4 v130, s[36:37]
	s_add_i32 m0, s65, 0x2000
	s_add_u32 s66, s36, 0x40000
	s_addc_u32 s67, s37, 0
	s_add_i32 s65, s51, s0
	global_load_lds_dwordx4 v134, s[36:37]
	s_mov_b32 m0, s65
	ds_read_b128 v[214:217], v153 offset:23552
	global_load_lds_dwordx4 v130, s[66:67]
	s_add_i32 m0, s65, 0x2000
	ds_read_b128 v[210:213], v153 offset:22528
	global_load_lds_dwordx4 v134, s[66:67]
	s_mov_b32 m0, s1
	ds_read_b128 v[206:209], v153 offset:21504
	global_load_lds_dwordx4 v128, s[40:41]
	s_mov_b32 m0, s31
	ds_read_b128 v[202:205], v153 offset:20480
	global_load_lds_dwordx4 v132, s[40:41]
	s_waitcnt vmcnt(8)
	s_waitcnt lgkmcnt(0)
	s_barrier
	s_setprio 1
	v_mfma_f32_16x16x32_bf16 v[60:63], v[144:147], v[182:185], v[60:63]
	v_mfma_f32_16x16x32_bf16 v[56:59], v[158:161], v[182:185], v[56:59]
	v_mfma_f32_16x16x32_bf16 v[44:47], v[144:147], v[194:197], v[44:47]
	v_mfma_f32_16x16x32_bf16 v[40:43], v[158:161], v[194:197], v[40:43]
	v_mfma_f32_16x16x32_bf16 v[28:31], v[144:147], v[202:205], v[28:31]
	v_mfma_f32_16x16x32_bf16 v[24:27], v[158:161], v[202:205], v[24:27]
	v_mfma_f32_16x16x32_bf16 v[12:15], v[144:147], v[210:213], v[12:15]
	v_mfma_f32_16x16x32_bf16 v[8:11], v[158:161], v[210:213], v[8:11]
	v_mfma_f32_16x16x32_bf16 v[60:63], v[154:157], v[186:189], v[60:63]
	v_mfma_f32_16x16x32_bf16 v[56:59], v[162:165], v[186:189], v[56:59]
	v_mfma_f32_16x16x32_bf16 v[44:47], v[154:157], v[198:201], v[44:47]
	v_mfma_f32_16x16x32_bf16 v[40:43], v[162:165], v[198:201], v[40:43]
	v_mfma_f32_16x16x32_bf16 v[28:31], v[154:157], v[206:209], v[28:31]
	v_mfma_f32_16x16x32_bf16 v[24:27], v[162:165], v[206:209], v[24:27]
	v_mfma_f32_16x16x32_bf16 v[12:15], v[154:157], v[214:217], v[12:15]
	v_mfma_f32_16x16x32_bf16 v[8:11], v[162:165], v[214:217], v[8:11]
	s_setprio 0
	s_setprio 1
	v_mfma_f32_16x16x32_bf16 v[52:55], v[166:169], v[182:185], v[52:55]
	v_mfma_f32_16x16x32_bf16 v[48:51], v[174:177], v[182:185], v[48:51]
	v_mfma_f32_16x16x32_bf16 v[36:39], v[166:169], v[194:197], v[36:39]
	v_mfma_f32_16x16x32_bf16 v[32:35], v[174:177], v[194:197], v[32:35]
	v_mfma_f32_16x16x32_bf16 v[20:23], v[166:169], v[202:205], v[20:23]
	v_mfma_f32_16x16x32_bf16 v[16:19], v[174:177], v[202:205], v[16:19]
	v_mfma_f32_16x16x32_bf16 v[4:7], v[166:169], v[210:213], v[4:7]
	v_mfma_f32_16x16x32_bf16 v[0:3], v[174:177], v[210:213], v[0:3]
	v_mfma_f32_16x16x32_bf16 v[52:55], v[170:173], v[186:189], v[52:55]
	v_mfma_f32_16x16x32_bf16 v[48:51], v[178:181], v[186:189], v[48:51]
	v_mfma_f32_16x16x32_bf16 v[36:39], v[170:173], v[198:201], v[36:39]
	v_mfma_f32_16x16x32_bf16 v[32:35], v[178:181], v[198:201], v[32:35]
	v_mfma_f32_16x16x32_bf16 v[20:23], v[170:173], v[206:209], v[20:23]
	v_mfma_f32_16x16x32_bf16 v[16:19], v[178:181], v[206:209], v[16:19]
	v_mfma_f32_16x16x32_bf16 v[4:7], v[170:173], v[214:217], v[4:7]
	v_mfma_f32_16x16x32_bf16 v[0:3], v[178:181], v[214:217], v[0:3]
	s_setprio 0
	s_barrier
; #define PG8_STAGE(bufoff, gbase, voff) do { _Pragma("unroll") for (int _i = 0; _i < 2; ++_i) \
;         __builtin_amdgcn_global_load_lds((const unsigned*)((const char*)(gbase) + (voff)[_i]), (PG8_LAS unsigned*)(lds + (bufoff) + ldsw + _i * 8192), 16, 0, 0); } while (0)
; #define PG8_LDA(dst, b, h) do { _Pragma("unroll") for (int m = 0; m < 4; ++m) _Pragma("unroll") for (int k = 0; k < 2; ++k) dst[m][k] = *(const PG8_LAS bf16x8*)(lds + PG8_SA(b, h) + aoff + m * 2048 + k * 1024); } while (0)
; #define PG8_LDB(dst, b, h) do { _Pragma("unroll") for (int n = 0; n < 2; ++n) _Pragma("unroll") for (int k = 0; k < 2; ++k) dst[n][k] = *(const PG8_LAS bf16x8*)(lds + PG8_SB(b, h) + boff + n * 2048 + k * 1024); } while (0)
; #define PG8_MMA(ai, bj, At, Bt) do { __builtin_amdgcn_s_setprio(1); _Pragma("unroll") for (int m = 0; m < 4; ++m) _Pragma("unroll") for (int n = 0; n < 2; ++n) _Pragma("unroll") for (int k = 0; k < 2; ++k) \
;         acc[ai][bj][m][n] = __builtin_amdgcn_mfma_f32_16x16x32_bf16(Bt[n][k], At[m][k], acc[ai][bj][m][n], 0, 0, 0); __builtin_amdgcn_s_setprio(0); } while (0)
; #define PG8_WAIT_V(n) asm volatile("s_waitcnt vmcnt(" #n ")" ::: "memory")
; #define PG8_WAIT_L(n) asm volatile("s_waitcnt lgkmcnt(" #n ")" ::: "memory")
; #define PG8_BAR __builtin_amdgcn_s_barrier()
; #define PG8_SCHED __builtin_amdgcn_sched_barrier(0)
; template <class Epi, class Sched, bool ALIGN_EPI = false, bool SP2 = false>
; __device__ __forceinline__ void gemm_phase(PG8_LAS unsigned char* lds, const Gemm g, const Sched& S, const Epi& E) {
;     ...
;             PG8_LDB(B0, 1, 0); PG8_LDB(B1, 1, 1); PG8_SCHED; PG8_LDA(At, 1, 0); PG8_STAGE(PG8_SA(0, 1), a2 + hstep, voffA);
;             PG8_WAIT_V(8); PG8_WAIT_L(0); PG8_BAR; PG8_MMA(0, 0, At, B0); PG8_MMA(0, 1, At, B1); PG8_BAR; PG8_SCHED;
;             PG8_LDA(At, 1, 1); PG8_STAGE(PG8_SB(1, 0), b3, voffB); PG8_STAGE(PG8_SB(1, 1), b3 + hstep, voffB); PG8_STAGE(PG8_SA(1, 0), a3, voffA);
;             PG8_WAIT_V(8); PG8_WAIT_L(0); PG8_BAR; PG8_MMA(1, 0, At, B0); PG8_MMA(1, 1, At, B1); PG8_BAR; PG8_SCHED;
;     ...
;         if constexpr (ALIGN_EPI) { if (wr == 0) PG8_BAR; }
	s_add_i32 s65, 0, 0x18000
	s_add_i32 s66, 0, 0x1c000
	ds_read_b128 v[144:147], v240
	ds_read_b128 v[154:157], v240 offset:1024
	ds_read_b128 v[158:161], v240 offset:2048
	ds_read_b128 v[162:165], v240 offset:3072
	ds_read_b128 v[166:169], v241
	ds_read_b128 v[170:173], v241 offset:1024
	ds_read_b128 v[174:177], v241 offset:2048
	ds_read_b128 v[178:181], v241 offset:3072
	s_add_u32 s40, s40, 0x40000
	s_addc_u32 s41, s41, 0
	s_mov_b32 m0, s38
	ds_read_b128 v[182:185], v153 offset:32768
	ds_read_b128 v[186:189], v153 offset:33792
	ds_read_b128 v[194:197], v153 offset:34816
	ds_read_b128 v[198:201], v153 offset:35840
	ds_read_b128 v[202:205], v153 offset:36864
	ds_read_b128 v[206:209], v153 offset:37888
	ds_read_b128 v[210:213], v153 offset:38912
	global_load_lds_dwordx4 v128, s[40:41]
	s_mov_b32 m0, s39
	ds_read_b128 v[214:217], v153 offset:39936
	global_load_lds_dwordx4 v132, s[40:41]
	s_waitcnt vmcnt(8)
	s_waitcnt lgkmcnt(0)
	s_barrier
	s_setprio 1
	v_mfma_f32_16x16x32_bf16 v[124:127], v[144:147], v[182:185], v[124:127]
	v_mfma_f32_16x16x32_bf16 v[120:123], v[158:161], v[182:185], v[120:123]
	v_mfma_f32_16x16x32_bf16 v[108:111], v[144:147], v[194:197], v[108:111]
	v_mfma_f32_16x16x32_bf16 v[104:107], v[158:161], v[194:197], v[104:107]
	v_mfma_f32_16x16x32_bf16 v[92:95], v[144:147], v[202:205], v[92:95]
	v_mfma_f32_16x16x32_bf16 v[88:91], v[158:161], v[202:205], v[88:91]
	v_mfma_f32_16x16x32_bf16 v[76:79], v[144:147], v[210:213], v[76:79]
	v_mfma_f32_16x16x32_bf16 v[72:75], v[158:161], v[210:213], v[72:75]
	v_mfma_f32_16x16x32_bf16 v[124:127], v[154:157], v[186:189], v[124:127]
	v_mfma_f32_16x16x32_bf16 v[120:123], v[162:165], v[186:189], v[120:123]
	v_mfma_f32_16x16x32_bf16 v[108:111], v[154:157], v[198:201], v[108:111]
	v_mfma_f32_16x16x32_bf16 v[104:107], v[162:165], v[198:201], v[104:107]
	v_mfma_f32_16x16x32_bf16 v[92:95], v[154:157], v[206:209], v[92:95]
	v_mfma_f32_16x16x32_bf16 v[88:91], v[162:165], v[206:209], v[88:91]
	v_mfma_f32_16x16x32_bf16 v[76:79], v[154:157], v[214:217], v[76:79]
	v_mfma_f32_16x16x32_bf16 v[72:75], v[162:165], v[214:217], v[72:75]
	s_setprio 0
	s_setprio 1
	v_mfma_f32_16x16x32_bf16 v[116:119], v[166:169], v[182:185], v[116:119]
	v_mfma_f32_16x16x32_bf16 v[112:115], v[174:177], v[182:185], v[112:115]
	v_mfma_f32_16x16x32_bf16 v[100:103], v[166:169], v[194:197], v[100:103]
	v_mfma_f32_16x16x32_bf16 v[96:99], v[174:177], v[194:197], v[96:99]
	v_mfma_f32_16x16x32_bf16 v[84:87], v[166:169], v[202:205], v[84:87]
	v_mfma_f32_16x16x32_bf16 v[80:83], v[174:177], v[202:205], v[80:83]
	v_mfma_f32_16x16x32_bf16 v[68:71], v[166:169], v[210:213], v[68:71]
	v_mfma_f32_16x16x32_bf16 v[64:67], v[174:177], v[210:213], v[64:67]
	v_mfma_f32_16x16x32_bf16 v[116:119], v[170:173], v[186:189], v[116:119]
	v_mfma_f32_16x16x32_bf16 v[112:115], v[178:181], v[186:189], v[112:115]
	v_mfma_f32_16x16x32_bf16 v[100:103], v[170:173], v[198:201], v[100:103]
	v_mfma_f32_16x16x32_bf16 v[96:99], v[178:181], v[198:201], v[96:99]
	v_mfma_f32_16x16x32_bf16 v[84:87], v[170:173], v[206:209], v[84:87]
	v_mfma_f32_16x16x32_bf16 v[80:83], v[178:181], v[206:209], v[80:83]
	v_mfma_f32_16x16x32_bf16 v[68:71], v[170:173], v[214:217], v[68:71]
	v_mfma_f32_16x16x32_bf16 v[64:67], v[178:181], v[214:217], v[64:67]
	s_setprio 0
	s_barrier
	s_add_i32 s40, s65, s0
	s_mov_b32 m0, s40
	ds_read_b128 v[182:185], v153 offset:49152
	ds_read_b128 v[186:189], v153 offset:50176
	ds_read_b128 v[194:197], v153 offset:51200
	ds_read_b128 v[198:201], v153 offset:52224
	global_load_lds_dwordx4 v130, vcc
	s_add_i32 m0, s40, 0x2000
	s_add_u32 s36, s36, 0x40080
	s_addc_u32 s37, s37, 0
	s_add_i32 s40, s66, s0
	global_load_lds_dwordx4 v134, vcc
	s_mov_b32 m0, s40
	ds_read_b128 v[214:217], v153 offset:56320
	global_load_lds_dwordx4 v130, s[36:37]
	s_add_i32 m0, s40, 0x2000
	ds_read_b128 v[210:213], v153 offset:55296
	global_load_lds_dwordx4 v134, s[36:37]
	s_mov_b32 m0, s44
	ds_read_b128 v[206:209], v153 offset:54272
	global_load_lds_dwordx4 v128, s[100:101]
	s_mov_b32 m0, s45
	ds_read_b128 v[202:205], v153 offset:53248
	global_load_lds_dwordx4 v132, s[100:101]
	s_waitcnt vmcnt(8)
	s_waitcnt lgkmcnt(0)
	s_barrier
	s_setprio 1
	v_mfma_f32_16x16x32_bf16 v[60:63], v[144:147], v[182:185], v[60:63]
	v_mfma_f32_16x16x32_bf16 v[56:59], v[158:161], v[182:185], v[56:59]
	v_mfma_f32_16x16x32_bf16 v[44:47], v[144:147], v[194:197], v[44:47]
	v_mfma_f32_16x16x32_bf16 v[40:43], v[158:161], v[194:197], v[40:43]
	v_mfma_f32_16x16x32_bf16 v[28:31], v[144:147], v[202:205], v[28:31]
	v_mfma_f32_16x16x32_bf16 v[24:27], v[158:161], v[202:205], v[24:27]
	v_mfma_f32_16x16x32_bf16 v[12:15], v[144:147], v[210:213], v[12:15]
	v_mfma_f32_16x16x32_bf16 v[8:11], v[158:161], v[210:213], v[8:11]
	v_mfma_f32_16x16x32_bf16 v[60:63], v[154:157], v[186:189], v[60:63]
	v_mfma_f32_16x16x32_bf16 v[56:59], v[162:165], v[186:189], v[56:59]
	v_mfma_f32_16x16x32_bf16 v[44:47], v[154:157], v[198:201], v[44:47]
	v_mfma_f32_16x16x32_bf16 v[40:43], v[162:165], v[198:201], v[40:43]
	v_mfma_f32_16x16x32_bf16 v[28:31], v[154:157], v[206:209], v[28:31]
	v_mfma_f32_16x16x32_bf16 v[24:27], v[162:165], v[206:209], v[24:27]
	v_mfma_f32_16x16x32_bf16 v[12:15], v[154:157], v[214:217], v[12:15]
	v_mfma_f32_16x16x32_bf16 v[8:11], v[162:165], v[214:217], v[8:11]
	s_setprio 0
	s_setprio 1
	v_mfma_f32_16x16x32_bf16 v[52:55], v[166:169], v[182:185], v[52:55]
	v_mfma_f32_16x16x32_bf16 v[48:51], v[174:177], v[182:185], v[48:51]
	v_mfma_f32_16x16x32_bf16 v[36:39], v[166:169], v[194:197], v[36:39]
	v_mfma_f32_16x16x32_bf16 v[32:35], v[174:177], v[194:197], v[32:35]
	v_mfma_f32_16x16x32_bf16 v[20:23], v[166:169], v[202:205], v[20:23]
	v_mfma_f32_16x16x32_bf16 v[16:19], v[174:177], v[202:205], v[16:19]
	v_mfma_f32_16x16x32_bf16 v[4:7], v[166:169], v[210:213], v[4:7]
	v_mfma_f32_16x16x32_bf16 v[0:3], v[174:177], v[210:213], v[0:3]
	v_mfma_f32_16x16x32_bf16 v[52:55], v[170:173], v[186:189], v[52:55]
	v_mfma_f32_16x16x32_bf16 v[48:51], v[178:181], v[186:189], v[48:51]
	v_mfma_f32_16x16x32_bf16 v[36:39], v[170:173], v[198:201], v[36:39]
	v_mfma_f32_16x16x32_bf16 v[32:35], v[178:181], v[198:201], v[32:35]
	v_mfma_f32_16x16x32_bf16 v[20:23], v[170:173], v[206:209], v[20:23]
	v_mfma_f32_16x16x32_bf16 v[16:19], v[178:181], v[206:209], v[16:19]
	v_mfma_f32_16x16x32_bf16 v[4:7], v[170:173], v[214:217], v[4:7]
	v_mfma_f32_16x16x32_bf16 v[0:3], v[178:181], v[214:217], v[0:3]
	s_setprio 0
	s_barrier
	s_add_i32 s64, s64, 2
	s_add_u32 s34, s34, 0x100
	s_addc_u32 s35, s35, 0
	s_add_u32 s62, s62, 0x100
	s_addc_u32 s63, s63, 0
	s_cmp_gt_u32 s64, 13
	s_cbranch_scc0 .LBB0_413
	s_and_b64 vcc, exec, s[18:19]
	s_cbranch_vccz .LBB0_416
	s_barrier

; #define PG8_STAGE(bufoff, gbase, voff) do { _Pragma("unroll") for (int _i = 0; _i < 2; ++_i) \
;         __builtin_amdgcn_global_load_lds((const unsigned*)((const char*)(gbase) + (voff)[_i]), (PG8_LAS unsigned*)(lds + (bufoff) + ldsw + _i * 8192), 16, 0, 0); } while (0)
; #define PG8_LDA(dst, b, h) do { _Pragma("unroll") for (int m = 0; m < 4; ++m) _Pragma("unroll") for (int k = 0; k < 2; ++k) dst[m][k] = *(const PG8_LAS bf16x8*)(lds + PG8_SA(b, h) + aoff + m * 2048 + k * 1024); } while (0)
; #define PG8_LDB(dst, b, h) do { _Pragma("unroll") for (int n = 0; n < 2; ++n) _Pragma("unroll") for (int k = 0; k < 2; ++k) dst[n][k] = *(const PG8_LAS bf16x8*)(lds + PG8_SB(b, h) + boff + n * 2048 + k * 1024); } while (0)
; #define PG8_MMA(ai, bj, At, Bt) do { __builtin_amdgcn_s_setprio(1); _Pragma("unroll") for (int m = 0; m < 4; ++m) _Pragma("unroll") for (int n = 0; n < 2; ++n) _Pragma("unroll") for (int k = 0; k < 2; ++k) \
;         acc[ai][bj][m][n] = __builtin_amdgcn_mfma_f32_16x16x32_bf16(Bt[n][k], At[m][k], acc[ai][bj][m][n], 0, 0, 0); __builtin_amdgcn_s_setprio(0); } while (0)
; #define PG8_WAIT_V(n) asm volatile("s_waitcnt vmcnt(" #n ")" ::: "memory")
; #define PG8_WAIT_L(n) asm volatile("s_waitcnt lgkmcnt(" #n ")" ::: "memory")
; #define PG8_BAR __builtin_amdgcn_s_barrier()
; #define PG8_SCHED __builtin_amdgcn_sched_barrier(0)
; template <class Epi, class Sched, bool ALIGN_EPI = false, bool SP2 = false>
; __device__ __forceinline__ void gemm_phase(PG8_LAS unsigned char* lds, const Gemm g, const Sched& S, const Epi& E) {
;     ...
;             PG8_LDB(B0, 0, 0); PG8_LDB(B1, 0, 1); PG8_SCHED; PG8_LDA(At, 0, 0); PG8_STAGE(PG8_SA(1, 1), a1 + hstep, voffA);
;             PG8_WAIT_V(8); PG8_WAIT_L(0); PG8_BAR; PG8_MMA(0, 0, At, B0); PG8_MMA(0, 1, At, B1); PG8_BAR; PG8_SCHED;
;             PG8_LDA(At, 0, 1); PG8_STAGE(PG8_SB(0, 0), b2, voffB); PG8_STAGE(PG8_SB(0, 1), b2 + hstep, voffB); PG8_STAGE(PG8_SA(0, 0), a2, voffA);
;             PG8_WAIT_V(8); PG8_WAIT_L(0); PG8_BAR; PG8_MMA(1, 0, At, B0); PG8_MMA(1, 1, At, B1); PG8_BAR; PG8_SCHED;
.LBB0_462:
	ds_read_b128 v[156:159], v151
	ds_read_b128 v[160:163], v151 offset:1024
	ds_read_b128 v[164:167], v151 offset:2048
	ds_read_b128 v[168:171], v151 offset:3072
	ds_read_b128 v[172:175], v152
	ds_read_b128 v[176:179], v152 offset:1024
	ds_read_b128 v[180:183], v152 offset:2048
	ds_read_b128 v[184:187], v152 offset:3072
	s_add_u32 s26, s24, 0xfffc0080
	s_addc_u32 s27, s25, -1
	s_cmp_eq_u32 s50, 12
	s_cselect_b32 s29, s17, s27
	s_cselect_b32 s28, s41, s26
	s_cselect_b32 s27, s11, s45
	s_cselect_b32 s26, s42, s44
	s_add_u32 vcc_lo, s26, 0x80
	s_addc_u32 vcc_hi, s27, 0
	s_add_u32 s100, s28, 0x80
	s_addc_u32 s101, s29, 0
	s_add_i32 m0, s1, 0xc000
	ds_read_b128 v[194:197], v153
	ds_read_b128 v[198:201], v153 offset:1024
	ds_read_b128 v[202:205], v153 offset:2048
	ds_read_b128 v[206:209], v153 offset:3072
	ds_read_b128 v[210:213], v153 offset:4096
	ds_read_b128 v[214:217], v153 offset:5120
	ds_read_b128 v[218:221], v153 offset:6144
	global_load_lds_dwordx4 v138, s[24:25]
	s_add_i32 m0, s1, 0xe000
	ds_read_b128 v[222:225], v153 offset:7168
	global_load_lds_dwordx4 v140, s[24:25]
	s_waitcnt vmcnt(8)
	s_waitcnt lgkmcnt(0)
	s_barrier
	s_setprio 1
	v_mfma_f32_16x16x32_bf16 v[124:127], v[156:159], v[194:197], v[124:127]
	v_mfma_f32_16x16x32_bf16 v[120:123], v[164:167], v[194:197], v[120:123]
	v_mfma_f32_16x16x32_bf16 v[108:111], v[156:159], v[202:205], v[108:111]
	v_mfma_f32_16x16x32_bf16 v[104:107], v[164:167], v[202:205], v[104:107]
	v_mfma_f32_16x16x32_bf16 v[92:95], v[156:159], v[210:213], v[92:95]
	v_mfma_f32_16x16x32_bf16 v[88:91], v[164:167], v[210:213], v[88:91]
	v_mfma_f32_16x16x32_bf16 v[76:79], v[156:159], v[218:221], v[76:79]
	v_mfma_f32_16x16x32_bf16 v[72:75], v[164:167], v[218:221], v[72:75]
	v_mfma_f32_16x16x32_bf16 v[124:127], v[160:163], v[198:201], v[124:127]
	v_mfma_f32_16x16x32_bf16 v[120:123], v[168:171], v[198:201], v[120:123]
	v_mfma_f32_16x16x32_bf16 v[108:111], v[160:163], v[206:209], v[108:111]
	v_mfma_f32_16x16x32_bf16 v[104:107], v[168:171], v[206:209], v[104:107]
	v_mfma_f32_16x16x32_bf16 v[92:95], v[160:163], v[214:217], v[92:95]
	v_mfma_f32_16x16x32_bf16 v[88:91], v[168:171], v[214:217], v[88:91]
	v_mfma_f32_16x16x32_bf16 v[76:79], v[160:163], v[222:225], v[76:79]
	v_mfma_f32_16x16x32_bf16 v[72:75], v[168:171], v[222:225], v[72:75]
	s_setprio 0
	s_setprio 1
	v_mfma_f32_16x16x32_bf16 v[116:119], v[172:175], v[194:197], v[116:119]
	v_mfma_f32_16x16x32_bf16 v[112:115], v[180:183], v[194:197], v[112:115]
	v_mfma_f32_16x16x32_bf16 v[100:103], v[172:175], v[202:205], v[100:103]
	v_mfma_f32_16x16x32_bf16 v[96:99], v[180:183], v[202:205], v[96:99]
	v_mfma_f32_16x16x32_bf16 v[84:87], v[172:175], v[210:213], v[84:87]
	v_mfma_f32_16x16x32_bf16 v[80:83], v[180:183], v[210:213], v[80:83]
	v_mfma_f32_16x16x32_bf16 v[68:71], v[172:175], v[218:221], v[68:71]
	v_mfma_f32_16x16x32_bf16 v[64:67], v[180:183], v[218:221], v[64:67]
	v_mfma_f32_16x16x32_bf16 v[116:119], v[176:179], v[198:201], v[116:119]
	v_mfma_f32_16x16x32_bf16 v[112:115], v[184:187], v[198:201], v[112:115]
	v_mfma_f32_16x16x32_bf16 v[100:103], v[176:179], v[206:209], v[100:103]
	v_mfma_f32_16x16x32_bf16 v[96:99], v[184:187], v[206:209], v[96:99]
	v_mfma_f32_16x16x32_bf16 v[84:87], v[176:179], v[214:217], v[84:87]
	v_mfma_f32_16x16x32_bf16 v[80:83], v[184:187], v[214:217], v[80:83]
	v_mfma_f32_16x16x32_bf16 v[68:71], v[176:179], v[222:225], v[68:71]
	v_mfma_f32_16x16x32_bf16 v[64:67], v[184:187], v[222:225], v[64:67]
	s_setprio 0
	s_barrier
	s_add_i32 s51, s38, s0
	s_mov_b32 m0, s51
	ds_read_b128 v[194:197], v153 offset:16384
	ds_read_b128 v[198:201], v153 offset:17408
	ds_read_b128 v[202:205], v153 offset:18432
	ds_read_b128 v[206:209], v153 offset:19456
	global_load_lds_dwordx4 v132, s[26:27]
	s_add_i32 m0, s51, 0x2000
	s_add_u32 s56, s26, 0x40000
	s_addc_u32 s57, s27, 0
	s_add_i32 s51, s39, s0
	global_load_lds_dwordx4 v128, s[26:27]
	s_mov_b32 m0, s51
	ds_read_b128 v[222:225], v153 offset:23552
	global_load_lds_dwordx4 v132, s[56:57]
	s_add_i32 m0, s51, 0x2000
	ds_read_b128 v[218:221], v153 offset:22528
	global_load_lds_dwordx4 v128, s[56:57]
	s_mov_b32 m0, s1
	ds_read_b128 v[214:217], v153 offset:21504
	global_load_lds_dwordx4 v134, s[28:29]
	s_mov_b32 m0, s23
	ds_read_b128 v[210:213], v153 offset:20480
	global_load_lds_dwordx4 v130, s[28:29]
	s_waitcnt vmcnt(8)
	s_waitcnt lgkmcnt(0)
	s_barrier
	s_setprio 1
	v_mfma_f32_16x16x32_bf16 v[60:63], v[156:159], v[194:197], v[60:63]
	v_mfma_f32_16x16x32_bf16 v[56:59], v[164:167], v[194:197], v[56:59]
	v_mfma_f32_16x16x32_bf16 v[44:47], v[156:159], v[202:205], v[44:47]
	v_mfma_f32_16x16x32_bf16 v[40:43], v[164:167], v[202:205], v[40:43]
	v_mfma_f32_16x16x32_bf16 v[28:31], v[156:159], v[210:213], v[28:31]
	v_mfma_f32_16x16x32_bf16 v[24:27], v[164:167], v[210:213], v[24:27]
	v_mfma_f32_16x16x32_bf16 v[12:15], v[156:159], v[218:221], v[12:15]
	v_mfma_f32_16x16x32_bf16 v[8:11], v[164:167], v[218:221], v[8:11]
	v_mfma_f32_16x16x32_bf16 v[60:63], v[160:163], v[198:201], v[60:63]
	v_mfma_f32_16x16x32_bf16 v[56:59], v[168:171], v[198:201], v[56:59]
	v_mfma_f32_16x16x32_bf16 v[44:47], v[160:163], v[206:209], v[44:47]
	v_mfma_f32_16x16x32_bf16 v[40:43], v[168:171], v[206:209], v[40:43]
	v_mfma_f32_16x16x32_bf16 v[28:31], v[160:163], v[214:217], v[28:31]
	v_mfma_f32_16x16x32_bf16 v[24:27], v[168:171], v[214:217], v[24:27]
	v_mfma_f32_16x16x32_bf16 v[12:15], v[160:163], v[222:225], v[12:15]
	v_mfma_f32_16x16x32_bf16 v[8:11], v[168:171], v[222:225], v[8:11]
	s_setprio 0
	s_setprio 1
	v_mfma_f32_16x16x32_bf16 v[52:55], v[172:175], v[194:197], v[52:55]
	v_mfma_f32_16x16x32_bf16 v[48:51], v[180:183], v[194:197], v[48:51]
	v_mfma_f32_16x16x32_bf16 v[36:39], v[172:175], v[202:205], v[36:39]
	v_mfma_f32_16x16x32_bf16 v[32:35], v[180:183], v[202:205], v[32:35]
	v_mfma_f32_16x16x32_bf16 v[20:23], v[172:175], v[210:213], v[20:23]
	v_mfma_f32_16x16x32_bf16 v[16:19], v[180:183], v[210:213], v[16:19]
	v_mfma_f32_16x16x32_bf16 v[4:7], v[172:175], v[218:221], v[4:7]
	v_mfma_f32_16x16x32_bf16 v[0:3], v[180:183], v[218:221], v[0:3]
	v_mfma_f32_16x16x32_bf16 v[52:55], v[176:179], v[198:201], v[52:55]
	v_mfma_f32_16x16x32_bf16 v[48:51], v[184:187], v[198:201], v[48:51]
	v_mfma_f32_16x16x32_bf16 v[36:39], v[176:179], v[206:209], v[36:39]
	v_mfma_f32_16x16x32_bf16 v[32:35], v[184:187], v[206:209], v[32:35]
	v_mfma_f32_16x16x32_bf16 v[20:23], v[176:179], v[214:217], v[20:23]
	v_mfma_f32_16x16x32_bf16 v[16:19], v[184:187], v[214:217], v[16:19]
	v_mfma_f32_16x16x32_bf16 v[4:7], v[176:179], v[222:225], v[4:7]
	v_mfma_f32_16x16x32_bf16 v[0:3], v[184:187], v[222:225], v[0:3]
	s_setprio 0
	s_barrier
; #define PG8_STAGE(bufoff, gbase, voff) do { _Pragma("unroll") for (int _i = 0; _i < 2; ++_i) \
;         __builtin_amdgcn_global_load_lds((const unsigned*)((const char*)(gbase) + (voff)[_i]), (PG8_LAS unsigned*)(lds + (bufoff) + ldsw + _i * 8192), 16, 0, 0); } while (0)
; #define PG8_LDA(dst, b, h) do { _Pragma("unroll") for (int m = 0; m < 4; ++m) _Pragma("unroll") for (int k = 0; k < 2; ++k) dst[m][k] = *(const PG8_LAS bf16x8*)(lds + PG8_SA(b, h) + aoff + m * 2048 + k * 1024); } while (0)
; #define PG8_LDB(dst, b, h) do { _Pragma("unroll") for (int n = 0; n < 2; ++n) _Pragma("unroll") for (int k = 0; k < 2; ++k) dst[n][k] = *(const PG8_LAS bf16x8*)(lds + PG8_SB(b, h) + boff + n * 2048 + k * 1024); } while (0)
; #define PG8_MMA(ai, bj, At, Bt) do { __builtin_amdgcn_s_setprio(1); _Pragma("unroll") for (int m = 0; m < 4; ++m) _Pragma("unroll") for (int n = 0; n < 2; ++n) _Pragma("unroll") for (int k = 0; k < 2; ++k) \
;         acc[ai][bj][m][n] = __builtin_amdgcn_mfma_f32_16x16x32_bf16(Bt[n][k], At[m][k], acc[ai][bj][m][n], 0, 0, 0); __builtin_amdgcn_s_setprio(0); } while (0)
; #define PG8_WAIT_V(n) asm volatile("s_waitcnt vmcnt(" #n ")" ::: "memory")
; #define PG8_WAIT_L(n) asm volatile("s_waitcnt lgkmcnt(" #n ")" ::: "memory")
; #define PG8_BAR __builtin_amdgcn_s_barrier()
; #define PG8_SCHED __builtin_amdgcn_sched_barrier(0)
; template <class Epi, class Sched, bool ALIGN_EPI = false, bool SP2 = false>
; __device__ __forceinline__ void gemm_phase(PG8_LAS unsigned char* lds, const Gemm g, const Sched& S, const Epi& E) {
;     ...
;             PG8_LDB(B0, 1, 0); PG8_LDB(B1, 1, 1); PG8_SCHED; PG8_LDA(At, 1, 0); PG8_STAGE(PG8_SA(0, 1), a2 + hstep, voffA);
;             PG8_WAIT_V(8); PG8_WAIT_L(0); PG8_BAR; PG8_MMA(0, 0, At, B0); PG8_MMA(0, 1, At, B1); PG8_BAR; PG8_SCHED;
;             PG8_LDA(At, 1, 1); PG8_STAGE(PG8_SB(1, 0), b3, voffB); PG8_STAGE(PG8_SB(1, 1), b3 + hstep, voffB); PG8_STAGE(PG8_SA(1, 0), a3, voffA);
;             PG8_WAIT_V(8); PG8_WAIT_L(0); PG8_BAR; PG8_MMA(1, 0, At, B0); PG8_MMA(1, 1, At, B1); PG8_BAR; PG8_SCHED;
;     ...
;         if constexpr (ALIGN_EPI) { if (wr == 0) PG8_BAR; }
	s_add_i32 s51, 0, 0x18000
	s_add_i32 s56, 0, 0x1c000
	ds_read_b128 v[156:159], v240
	ds_read_b128 v[160:163], v240 offset:1024
	ds_read_b128 v[164:167], v240 offset:2048
	ds_read_b128 v[168:171], v240 offset:3072
	ds_read_b128 v[172:175], v241
	ds_read_b128 v[176:179], v241 offset:1024
	ds_read_b128 v[180:183], v241 offset:2048
	ds_read_b128 v[184:187], v241 offset:3072
	s_add_u32 s28, s28, 0x40000
	s_addc_u32 s29, s29, 0
	s_mov_b32 m0, s31
	ds_read_b128 v[194:197], v153 offset:32768
	ds_read_b128 v[198:201], v153 offset:33792
	ds_read_b128 v[202:205], v153 offset:34816
	ds_read_b128 v[206:209], v153 offset:35840
	ds_read_b128 v[210:213], v153 offset:36864
	ds_read_b128 v[214:217], v153 offset:37888
	ds_read_b128 v[218:221], v153 offset:38912
	global_load_lds_dwordx4 v134, s[28:29]
	s_mov_b32 m0, s34
	ds_read_b128 v[222:225], v153 offset:39936
	global_load_lds_dwordx4 v130, s[28:29]
	s_waitcnt vmcnt(8)
	s_waitcnt lgkmcnt(0)
	s_barrier
	s_setprio 1
	v_mfma_f32_16x16x32_bf16 v[124:127], v[156:159], v[194:197], v[124:127]
	v_mfma_f32_16x16x32_bf16 v[120:123], v[164:167], v[194:197], v[120:123]
	v_mfma_f32_16x16x32_bf16 v[108:111], v[156:159], v[202:205], v[108:111]
	v_mfma_f32_16x16x32_bf16 v[104:107], v[164:167], v[202:205], v[104:107]
	v_mfma_f32_16x16x32_bf16 v[92:95], v[156:159], v[210:213], v[92:95]
	v_mfma_f32_16x16x32_bf16 v[88:91], v[164:167], v[210:213], v[88:91]
	v_mfma_f32_16x16x32_bf16 v[76:79], v[156:159], v[218:221], v[76:79]
	v_mfma_f32_16x16x32_bf16 v[72:75], v[164:167], v[218:221], v[72:75]
	v_mfma_f32_16x16x32_bf16 v[124:127], v[160:163], v[198:201], v[124:127]
	v_mfma_f32_16x16x32_bf16 v[120:123], v[168:171], v[198:201], v[120:123]
	v_mfma_f32_16x16x32_bf16 v[108:111], v[160:163], v[206:209], v[108:111]
	v_mfma_f32_16x16x32_bf16 v[104:107], v[168:171], v[206:209], v[104:107]
	v_mfma_f32_16x16x32_bf16 v[92:95], v[160:163], v[214:217], v[92:95]
	v_mfma_f32_16x16x32_bf16 v[88:91], v[168:171], v[214:217], v[88:91]
	v_mfma_f32_16x16x32_bf16 v[76:79], v[160:163], v[222:225], v[76:79]
	v_mfma_f32_16x16x32_bf16 v[72:75], v[168:171], v[222:225], v[72:75]
	s_setprio 0
	s_setprio 1
	v_mfma_f32_16x16x32_bf16 v[116:119], v[172:175], v[194:197], v[116:119]
	v_mfma_f32_16x16x32_bf16 v[112:115], v[180:183], v[194:197], v[112:115]
	v_mfma_f32_16x16x32_bf16 v[100:103], v[172:175], v[202:205], v[100:103]
	v_mfma_f32_16x16x32_bf16 v[96:99], v[180:183], v[202:205], v[96:99]
	v_mfma_f32_16x16x32_bf16 v[84:87], v[172:175], v[210:213], v[84:87]
	v_mfma_f32_16x16x32_bf16 v[80:83], v[180:183], v[210:213], v[80:83]
	v_mfma_f32_16x16x32_bf16 v[68:71], v[172:175], v[218:221], v[68:71]
	v_mfma_f32_16x16x32_bf16 v[64:67], v[180:183], v[218:221], v[64:67]
	v_mfma_f32_16x16x32_bf16 v[116:119], v[176:179], v[198:201], v[116:119]
	v_mfma_f32_16x16x32_bf16 v[112:115], v[184:187], v[198:201], v[112:115]
	v_mfma_f32_16x16x32_bf16 v[100:103], v[176:179], v[206:209], v[100:103]
	v_mfma_f32_16x16x32_bf16 v[96:99], v[184:187], v[206:209], v[96:99]
	v_mfma_f32_16x16x32_bf16 v[84:87], v[176:179], v[214:217], v[84:87]
	v_mfma_f32_16x16x32_bf16 v[80:83], v[184:187], v[214:217], v[80:83]
	v_mfma_f32_16x16x32_bf16 v[68:71], v[176:179], v[222:225], v[68:71]
	v_mfma_f32_16x16x32_bf16 v[64:67], v[184:187], v[222:225], v[64:67]
	s_setprio 0
	s_barrier
	s_add_i32 s28, s51, s0
	s_mov_b32 m0, s28
	ds_read_b128 v[194:197], v153 offset:49152
	ds_read_b128 v[198:201], v153 offset:50176
	ds_read_b128 v[202:205], v153 offset:51200
	ds_read_b128 v[206:209], v153 offset:52224
	global_load_lds_dwordx4 v132, vcc
	s_add_i32 m0, s28, 0x2000
	s_add_u32 s26, s26, 0x40080
	s_addc_u32 s27, s27, 0
	s_add_i32 s28, s56, s0
	global_load_lds_dwordx4 v128, vcc
	s_mov_b32 m0, s28
	ds_read_b128 v[222:225], v153 offset:56320
	global_load_lds_dwordx4 v132, s[26:27]
	s_add_i32 m0, s28, 0x2000
	ds_read_b128 v[218:221], v153 offset:55296
	global_load_lds_dwordx4 v128, s[26:27]
	s_mov_b32 m0, s36
	ds_read_b128 v[214:217], v153 offset:54272
	global_load_lds_dwordx4 v134, s[100:101]
	s_mov_b32 m0, s37
	ds_read_b128 v[210:213], v153 offset:53248
	global_load_lds_dwordx4 v130, s[100:101]
	s_waitcnt vmcnt(8)
	s_waitcnt lgkmcnt(0)
	s_barrier
	s_setprio 1
	v_mfma_f32_16x16x32_bf16 v[60:63], v[156:159], v[194:197], v[60:63]
	v_mfma_f32_16x16x32_bf16 v[56:59], v[164:167], v[194:197], v[56:59]
	v_mfma_f32_16x16x32_bf16 v[44:47], v[156:159], v[202:205], v[44:47]
	v_mfma_f32_16x16x32_bf16 v[40:43], v[164:167], v[202:205], v[40:43]
	v_mfma_f32_16x16x32_bf16 v[28:31], v[156:159], v[210:213], v[28:31]
	v_mfma_f32_16x16x32_bf16 v[24:27], v[164:167], v[210:213], v[24:27]
	v_mfma_f32_16x16x32_bf16 v[12:15], v[156:159], v[218:221], v[12:15]
	v_mfma_f32_16x16x32_bf16 v[8:11], v[164:167], v[218:221], v[8:11]
	v_mfma_f32_16x16x32_bf16 v[60:63], v[160:163], v[198:201], v[60:63]
	v_mfma_f32_16x16x32_bf16 v[56:59], v[168:171], v[198:201], v[56:59]
	v_mfma_f32_16x16x32_bf16 v[44:47], v[160:163], v[206:209], v[44:47]
	v_mfma_f32_16x16x32_bf16 v[40:43], v[168:171], v[206:209], v[40:43]
	v_mfma_f32_16x16x32_bf16 v[28:31], v[160:163], v[214:217], v[28:31]
	v_mfma_f32_16x16x32_bf16 v[24:27], v[168:171], v[214:217], v[24:27]
	v_mfma_f32_16x16x32_bf16 v[12:15], v[160:163], v[222:225], v[12:15]
	v_mfma_f32_16x16x32_bf16 v[8:11], v[168:171], v[222:225], v[8:11]
	s_setprio 0
	s_setprio 1
	v_mfma_f32_16x16x32_bf16 v[52:55], v[172:175], v[194:197], v[52:55]
	v_mfma_f32_16x16x32_bf16 v[48:51], v[180:183], v[194:197], v[48:51]
	v_mfma_f32_16x16x32_bf16 v[36:39], v[172:175], v[202:205], v[36:39]
	v_mfma_f32_16x16x32_bf16 v[32:35], v[180:183], v[202:205], v[32:35]
	v_mfma_f32_16x16x32_bf16 v[20:23], v[172:175], v[210:213], v[20:23]
	v_mfma_f32_16x16x32_bf16 v[16:19], v[180:183], v[210:213], v[16:19]
	v_mfma_f32_16x16x32_bf16 v[4:7], v[172:175], v[218:221], v[4:7]
	v_mfma_f32_16x16x32_bf16 v[0:3], v[180:183], v[218:221], v[0:3]
	v_mfma_f32_16x16x32_bf16 v[52:55], v[176:179], v[198:201], v[52:55]
	v_mfma_f32_16x16x32_bf16 v[48:51], v[184:187], v[198:201], v[48:51]
	v_mfma_f32_16x16x32_bf16 v[36:39], v[176:179], v[206:209], v[36:39]
	v_mfma_f32_16x16x32_bf16 v[32:35], v[184:187], v[206:209], v[32:35]
	v_mfma_f32_16x16x32_bf16 v[20:23], v[176:179], v[214:217], v[20:23]
	v_mfma_f32_16x16x32_bf16 v[16:19], v[184:187], v[214:217], v[16:19]
	v_mfma_f32_16x16x32_bf16 v[4:7], v[176:179], v[222:225], v[4:7]
	v_mfma_f32_16x16x32_bf16 v[0:3], v[184:187], v[222:225], v[0:3]
	s_setprio 0
	s_barrier
	s_add_i32 s50, s50, 2
	s_add_u32 s24, s24, 0x100
	s_addc_u32 s25, s25, 0
	s_add_u32 s44, s44, 0x100
	s_addc_u32 s45, s45, 0
	s_cmp_gt_u32 s50, 13
	s_cbranch_scc0 .LBB0_462
	s_and_b64 vcc, exec, s[14:15]
	s_cbranch_vccz .LBB0_465
	s_barrier

; #define PG8_STAGE(bufoff, gbase, voff) do { _Pragma("unroll") for (int _i = 0; _i < 2; ++_i) \
;         __builtin_amdgcn_global_load_lds((const unsigned*)((const char*)(gbase) + (voff)[_i]), (PG8_LAS unsigned*)(lds + (bufoff) + ldsw + _i * 8192), 16, 0, 0); } while (0)
; #define PG8_LDA(dst, b, h) do { _Pragma("unroll") for (int m = 0; m < 4; ++m) _Pragma("unroll") for (int k = 0; k < 2; ++k) dst[m][k] = *(const PG8_LAS bf16x8*)(lds + PG8_SA(b, h) + aoff + m * 2048 + k * 1024); } while (0)
; #define PG8_LDB(dst, b, h) do { _Pragma("unroll") for (int n = 0; n < 2; ++n) _Pragma("unroll") for (int k = 0; k < 2; ++k) dst[n][k] = *(const PG8_LAS bf16x8*)(lds + PG8_SB(b, h) + boff + n * 2048 + k * 1024); } while (0)
; #define PG8_MMA(ai, bj, At, Bt) do { __builtin_amdgcn_s_setprio(1); _Pragma("unroll") for (int m = 0; m < 4; ++m) _Pragma("unroll") for (int n = 0; n < 2; ++n) _Pragma("unroll") for (int k = 0; k < 2; ++k) \
;         acc[ai][bj][m][n] = __builtin_amdgcn_mfma_f32_16x16x32_bf16(Bt[n][k], At[m][k], acc[ai][bj][m][n], 0, 0, 0); __builtin_amdgcn_s_setprio(0); } while (0)
; #define PG8_WAIT_V(n) asm volatile("s_waitcnt vmcnt(" #n ")" ::: "memory")
; #define PG8_WAIT_L(n) asm volatile("s_waitcnt lgkmcnt(" #n ")" ::: "memory")
; #define PG8_BAR __builtin_amdgcn_s_barrier()
; #define PG8_SCHED __builtin_amdgcn_sched_barrier(0)
; template <class Epi, class Sched, bool ALIGN_EPI = false, bool SP2 = false>
; __device__ __forceinline__ void gemm_phase(PG8_LAS unsigned char* lds, const Gemm g, const Sched& S, const Epi& E) {
;     ...
;             PG8_LDB(B0, 0, 0); PG8_LDB(B1, 0, 1); PG8_SCHED; PG8_LDA(At, 0, 0); PG8_STAGE(PG8_SA(1, 1), a1 + hstep, voffA);
;             PG8_WAIT_V(8); PG8_WAIT_L(0); PG8_BAR; PG8_MMA(0, 0, At, B0); PG8_MMA(0, 1, At, B1); PG8_BAR; PG8_SCHED;
;             PG8_LDA(At, 0, 1); PG8_STAGE(PG8_SB(0, 0), b2, voffB); PG8_STAGE(PG8_SB(0, 1), b2 + hstep, voffB); PG8_STAGE(PG8_SA(0, 0), a2, voffA);
;             PG8_WAIT_V(8); PG8_WAIT_L(0); PG8_BAR; PG8_MMA(1, 0, At, B0); PG8_MMA(1, 1, At, B1); PG8_BAR; PG8_SCHED;
.LBB0_501:
	ds_read_b128 v[144:147], v151
	ds_read_b128 v[154:157], v151 offset:1024
	ds_read_b128 v[158:161], v151 offset:2048
	ds_read_b128 v[162:165], v151 offset:3072
	ds_read_b128 v[166:169], v152
	ds_read_b128 v[170:173], v152 offset:1024
	ds_read_b128 v[174:177], v152 offset:2048
	ds_read_b128 v[178:181], v152 offset:3072
	s_add_u32 s28, s26, 0xfff00080
	s_addc_u32 s29, s27, -1
	s_cmp_eq_u32 s56, 60
	s_cselect_b32 s35, s19, s29
	s_cselect_b32 s34, s25, s28
	s_cselect_b32 s29, s17, s51
	s_cselect_b32 s28, s45, s50
	s_add_u32 vcc_lo, s28, 0x80
	s_addc_u32 vcc_hi, s29, 0
	s_add_u32 s100, s34, 0x80
	s_addc_u32 s101, s35, 0
	s_add_i32 m0, s1, 0xc000
	ds_read_b128 v[182:185], v153
	ds_read_b128 v[186:189], v153 offset:1024
	ds_read_b128 v[194:197], v153 offset:2048
	ds_read_b128 v[198:201], v153 offset:3072
	ds_read_b128 v[202:205], v153 offset:4096
	ds_read_b128 v[206:209], v153 offset:5120
	ds_read_b128 v[210:213], v153 offset:6144
	global_load_lds_dwordx4 v136, s[26:27]
	s_add_i32 m0, s1, 0xe000
	ds_read_b128 v[214:217], v153 offset:7168
	global_load_lds_dwordx4 v138, s[26:27]
	s_waitcnt vmcnt(8)
	s_waitcnt lgkmcnt(0)
	s_barrier
	s_setprio 1
	v_mfma_f32_16x16x32_bf16 v[124:127], v[144:147], v[182:185], v[124:127]
	v_mfma_f32_16x16x32_bf16 v[120:123], v[158:161], v[182:185], v[120:123]
	v_mfma_f32_16x16x32_bf16 v[108:111], v[144:147], v[194:197], v[108:111]
	v_mfma_f32_16x16x32_bf16 v[104:107], v[158:161], v[194:197], v[104:107]
	v_mfma_f32_16x16x32_bf16 v[92:95], v[144:147], v[202:205], v[92:95]
	v_mfma_f32_16x16x32_bf16 v[88:91], v[158:161], v[202:205], v[88:91]
	v_mfma_f32_16x16x32_bf16 v[76:79], v[144:147], v[210:213], v[76:79]
	v_mfma_f32_16x16x32_bf16 v[72:75], v[158:161], v[210:213], v[72:75]
	v_mfma_f32_16x16x32_bf16 v[124:127], v[154:157], v[186:189], v[124:127]
	v_mfma_f32_16x16x32_bf16 v[120:123], v[162:165], v[186:189], v[120:123]
	v_mfma_f32_16x16x32_bf16 v[108:111], v[154:157], v[198:201], v[108:111]
	v_mfma_f32_16x16x32_bf16 v[104:107], v[162:165], v[198:201], v[104:107]
	v_mfma_f32_16x16x32_bf16 v[92:95], v[154:157], v[206:209], v[92:95]
	v_mfma_f32_16x16x32_bf16 v[88:91], v[162:165], v[206:209], v[88:91]
	v_mfma_f32_16x16x32_bf16 v[76:79], v[154:157], v[214:217], v[76:79]
	v_mfma_f32_16x16x32_bf16 v[72:75], v[162:165], v[214:217], v[72:75]
	s_setprio 0
	s_setprio 1
	v_mfma_f32_16x16x32_bf16 v[116:119], v[166:169], v[182:185], v[116:119]
	v_mfma_f32_16x16x32_bf16 v[112:115], v[174:177], v[182:185], v[112:115]
	v_mfma_f32_16x16x32_bf16 v[100:103], v[166:169], v[194:197], v[100:103]
	v_mfma_f32_16x16x32_bf16 v[96:99], v[174:177], v[194:197], v[96:99]
	v_mfma_f32_16x16x32_bf16 v[84:87], v[166:169], v[202:205], v[84:87]
	v_mfma_f32_16x16x32_bf16 v[80:83], v[174:177], v[202:205], v[80:83]
	v_mfma_f32_16x16x32_bf16 v[68:71], v[166:169], v[210:213], v[68:71]
	v_mfma_f32_16x16x32_bf16 v[64:67], v[174:177], v[210:213], v[64:67]
	v_mfma_f32_16x16x32_bf16 v[116:119], v[170:173], v[186:189], v[116:119]
	v_mfma_f32_16x16x32_bf16 v[112:115], v[178:181], v[186:189], v[112:115]
	v_mfma_f32_16x16x32_bf16 v[100:103], v[170:173], v[198:201], v[100:103]
	v_mfma_f32_16x16x32_bf16 v[96:99], v[178:181], v[198:201], v[96:99]
	v_mfma_f32_16x16x32_bf16 v[84:87], v[170:173], v[206:209], v[84:87]
	v_mfma_f32_16x16x32_bf16 v[80:83], v[178:181], v[206:209], v[80:83]
	v_mfma_f32_16x16x32_bf16 v[68:71], v[170:173], v[214:217], v[68:71]
	v_mfma_f32_16x16x32_bf16 v[64:67], v[178:181], v[214:217], v[64:67]
	s_setprio 0
	s_barrier
	s_add_i32 s57, s41, s0
	s_mov_b32 m0, s57
	ds_read_b128 v[182:185], v153 offset:16384
	ds_read_b128 v[186:189], v153 offset:17408
	ds_read_b128 v[194:197], v153 offset:18432
	ds_read_b128 v[198:201], v153 offset:19456
	global_load_lds_dwordx4 v130, s[28:29]
	s_add_i32 m0, s57, 0x2000
	s_add_u32 s58, s28, 0x100000
	s_addc_u32 s59, s29, 0
	s_add_i32 s57, s42, s0
	global_load_lds_dwordx4 v134, s[28:29]
	s_mov_b32 m0, s57
	ds_read_b128 v[214:217], v153 offset:23552
	global_load_lds_dwordx4 v130, s[58:59]
	s_add_i32 m0, s57, 0x2000
	ds_read_b128 v[210:213], v153 offset:22528
	global_load_lds_dwordx4 v134, s[58:59]
	s_mov_b32 m0, s1
	ds_read_b128 v[206:209], v153 offset:21504
	global_load_lds_dwordx4 v128, s[34:35]
	s_mov_b32 m0, s31
	ds_read_b128 v[202:205], v153 offset:20480
	global_load_lds_dwordx4 v132, s[34:35]
	s_waitcnt vmcnt(8)
	s_waitcnt lgkmcnt(0)
	s_barrier
	s_setprio 1
	v_mfma_f32_16x16x32_bf16 v[60:63], v[144:147], v[182:185], v[60:63]
	v_mfma_f32_16x16x32_bf16 v[56:59], v[158:161], v[182:185], v[56:59]
	v_mfma_f32_16x16x32_bf16 v[44:47], v[144:147], v[194:197], v[44:47]
	v_mfma_f32_16x16x32_bf16 v[40:43], v[158:161], v[194:197], v[40:43]
	v_mfma_f32_16x16x32_bf16 v[28:31], v[144:147], v[202:205], v[28:31]
	v_mfma_f32_16x16x32_bf16 v[24:27], v[158:161], v[202:205], v[24:27]
	v_mfma_f32_16x16x32_bf16 v[12:15], v[144:147], v[210:213], v[12:15]
	v_mfma_f32_16x16x32_bf16 v[8:11], v[158:161], v[210:213], v[8:11]
	v_mfma_f32_16x16x32_bf16 v[60:63], v[154:157], v[186:189], v[60:63]
	v_mfma_f32_16x16x32_bf16 v[56:59], v[162:165], v[186:189], v[56:59]
	v_mfma_f32_16x16x32_bf16 v[44:47], v[154:157], v[198:201], v[44:47]
	v_mfma_f32_16x16x32_bf16 v[40:43], v[162:165], v[198:201], v[40:43]
	v_mfma_f32_16x16x32_bf16 v[28:31], v[154:157], v[206:209], v[28:31]
	v_mfma_f32_16x16x32_bf16 v[24:27], v[162:165], v[206:209], v[24:27]
	v_mfma_f32_16x16x32_bf16 v[12:15], v[154:157], v[214:217], v[12:15]
	v_mfma_f32_16x16x32_bf16 v[8:11], v[162:165], v[214:217], v[8:11]
	s_setprio 0
	s_setprio 1
	v_mfma_f32_16x16x32_bf16 v[52:55], v[166:169], v[182:185], v[52:55]
	v_mfma_f32_16x16x32_bf16 v[48:51], v[174:177], v[182:185], v[48:51]
	v_mfma_f32_16x16x32_bf16 v[36:39], v[166:169], v[194:197], v[36:39]
	v_mfma_f32_16x16x32_bf16 v[32:35], v[174:177], v[194:197], v[32:35]
	v_mfma_f32_16x16x32_bf16 v[20:23], v[166:169], v[202:205], v[20:23]
	v_mfma_f32_16x16x32_bf16 v[16:19], v[174:177], v[202:205], v[16:19]
	v_mfma_f32_16x16x32_bf16 v[4:7], v[166:169], v[210:213], v[4:7]
	v_mfma_f32_16x16x32_bf16 v[0:3], v[174:177], v[210:213], v[0:3]
	v_mfma_f32_16x16x32_bf16 v[52:55], v[170:173], v[186:189], v[52:55]
	v_mfma_f32_16x16x32_bf16 v[48:51], v[178:181], v[186:189], v[48:51]
	v_mfma_f32_16x16x32_bf16 v[36:39], v[170:173], v[198:201], v[36:39]
	v_mfma_f32_16x16x32_bf16 v[32:35], v[178:181], v[198:201], v[32:35]
	v_mfma_f32_16x16x32_bf16 v[20:23], v[170:173], v[206:209], v[20:23]
	v_mfma_f32_16x16x32_bf16 v[16:19], v[178:181], v[206:209], v[16:19]
	v_mfma_f32_16x16x32_bf16 v[4:7], v[170:173], v[214:217], v[4:7]
	v_mfma_f32_16x16x32_bf16 v[0:3], v[178:181], v[214:217], v[0:3]
	s_setprio 0
	s_barrier
; #define PG8_STAGE(bufoff, gbase, voff) do { _Pragma("unroll") for (int _i = 0; _i < 2; ++_i) \
;         __builtin_amdgcn_global_load_lds((const unsigned*)((const char*)(gbase) + (voff)[_i]), (PG8_LAS unsigned*)(lds + (bufoff) + ldsw + _i * 8192), 16, 0, 0); } while (0)
; #define PG8_LDA(dst, b, h) do { _Pragma("unroll") for (int m = 0; m < 4; ++m) _Pragma("unroll") for (int k = 0; k < 2; ++k) dst[m][k] = *(const PG8_LAS bf16x8*)(lds + PG8_SA(b, h) + aoff + m * 2048 + k * 1024); } while (0)
; #define PG8_LDB(dst, b, h) do { _Pragma("unroll") for (int n = 0; n < 2; ++n) _Pragma("unroll") for (int k = 0; k < 2; ++k) dst[n][k] = *(const PG8_LAS bf16x8*)(lds + PG8_SB(b, h) + boff + n * 2048 + k * 1024); } while (0)
; #define PG8_MMA(ai, bj, At, Bt) do { __builtin_amdgcn_s_setprio(1); _Pragma("unroll") for (int m = 0; m < 4; ++m) _Pragma("unroll") for (int n = 0; n < 2; ++n) _Pragma("unroll") for (int k = 0; k < 2; ++k) \
;         acc[ai][bj][m][n] = __builtin_amdgcn_mfma_f32_16x16x32_bf16(Bt[n][k], At[m][k], acc[ai][bj][m][n], 0, 0, 0); __builtin_amdgcn_s_setprio(0); } while (0)
; #define PG8_WAIT_V(n) asm volatile("s_waitcnt vmcnt(" #n ")" ::: "memory")
; #define PG8_WAIT_L(n) asm volatile("s_waitcnt lgkmcnt(" #n ")" ::: "memory")
; #define PG8_BAR __builtin_amdgcn_s_barrier()
; #define PG8_SCHED __builtin_amdgcn_sched_barrier(0)
; template <class Epi, class Sched, bool ALIGN_EPI = false, bool SP2 = false>
; __device__ __forceinline__ void gemm_phase(PG8_LAS unsigned char* lds, const Gemm g, const Sched& S, const Epi& E) {
;     ...
;             PG8_LDB(B0, 1, 0); PG8_LDB(B1, 1, 1); PG8_SCHED; PG8_LDA(At, 1, 0); PG8_STAGE(PG8_SA(0, 1), a2 + hstep, voffA);
;             PG8_WAIT_V(8); PG8_WAIT_L(0); PG8_BAR; PG8_MMA(0, 0, At, B0); PG8_MMA(0, 1, At, B1); PG8_BAR; PG8_SCHED;
;             PG8_LDA(At, 1, 1); PG8_STAGE(PG8_SB(1, 0), b3, voffB); PG8_STAGE(PG8_SB(1, 1), b3 + hstep, voffB); PG8_STAGE(PG8_SA(1, 0), a3, voffA);
;             PG8_WAIT_V(8); PG8_WAIT_L(0); PG8_BAR; PG8_MMA(1, 0, At, B0); PG8_MMA(1, 1, At, B1); PG8_BAR; PG8_SCHED;
;     ...
;         if constexpr (ALIGN_EPI) { if (wr == 0) PG8_BAR; }
	s_add_i32 s57, 0, 0x18000
	s_add_i32 s58, 0, 0x1c000
	ds_read_b128 v[144:147], v240
	ds_read_b128 v[154:157], v240 offset:1024
	ds_read_b128 v[158:161], v240 offset:2048
	ds_read_b128 v[162:165], v240 offset:3072
	ds_read_b128 v[166:169], v241
	ds_read_b128 v[170:173], v241 offset:1024
	ds_read_b128 v[174:177], v241 offset:2048
	ds_read_b128 v[178:181], v241 offset:3072
	s_add_u32 s34, s34, 0x100000
	s_addc_u32 s35, s35, 0
	s_mov_b32 m0, s36
	ds_read_b128 v[182:185], v153 offset:32768
	ds_read_b128 v[186:189], v153 offset:33792
	ds_read_b128 v[194:197], v153 offset:34816
	ds_read_b128 v[198:201], v153 offset:35840
	ds_read_b128 v[202:205], v153 offset:36864
	ds_read_b128 v[206:209], v153 offset:37888
	ds_read_b128 v[210:213], v153 offset:38912
	global_load_lds_dwordx4 v128, s[34:35]
	s_mov_b32 m0, s37
	ds_read_b128 v[214:217], v153 offset:39936
	global_load_lds_dwordx4 v132, s[34:35]
	s_waitcnt vmcnt(8)
	s_waitcnt lgkmcnt(0)
	s_barrier
	s_setprio 1
	v_mfma_f32_16x16x32_bf16 v[124:127], v[144:147], v[182:185], v[124:127]
	v_mfma_f32_16x16x32_bf16 v[120:123], v[158:161], v[182:185], v[120:123]
	v_mfma_f32_16x16x32_bf16 v[108:111], v[144:147], v[194:197], v[108:111]
	v_mfma_f32_16x16x32_bf16 v[104:107], v[158:161], v[194:197], v[104:107]
	v_mfma_f32_16x16x32_bf16 v[92:95], v[144:147], v[202:205], v[92:95]
	v_mfma_f32_16x16x32_bf16 v[88:91], v[158:161], v[202:205], v[88:91]
	v_mfma_f32_16x16x32_bf16 v[76:79], v[144:147], v[210:213], v[76:79]
	v_mfma_f32_16x16x32_bf16 v[72:75], v[158:161], v[210:213], v[72:75]
	v_mfma_f32_16x16x32_bf16 v[124:127], v[154:157], v[186:189], v[124:127]
	v_mfma_f32_16x16x32_bf16 v[120:123], v[162:165], v[186:189], v[120:123]
	v_mfma_f32_16x16x32_bf16 v[108:111], v[154:157], v[198:201], v[108:111]
	v_mfma_f32_16x16x32_bf16 v[104:107], v[162:165], v[198:201], v[104:107]
	v_mfma_f32_16x16x32_bf16 v[92:95], v[154:157], v[206:209], v[92:95]
	v_mfma_f32_16x16x32_bf16 v[88:91], v[162:165], v[206:209], v[88:91]
	v_mfma_f32_16x16x32_bf16 v[76:79], v[154:157], v[214:217], v[76:79]
	v_mfma_f32_16x16x32_bf16 v[72:75], v[162:165], v[214:217], v[72:75]
	s_setprio 0
	s_setprio 1
	v_mfma_f32_16x16x32_bf16 v[116:119], v[166:169], v[182:185], v[116:119]
	v_mfma_f32_16x16x32_bf16 v[112:115], v[174:177], v[182:185], v[112:115]
	v_mfma_f32_16x16x32_bf16 v[100:103], v[166:169], v[194:197], v[100:103]
	v_mfma_f32_16x16x32_bf16 v[96:99], v[174:177], v[194:197], v[96:99]
	v_mfma_f32_16x16x32_bf16 v[84:87], v[166:169], v[202:205], v[84:87]
	v_mfma_f32_16x16x32_bf16 v[80:83], v[174:177], v[202:205], v[80:83]
	v_mfma_f32_16x16x32_bf16 v[68:71], v[166:169], v[210:213], v[68:71]
	v_mfma_f32_16x16x32_bf16 v[64:67], v[174:177], v[210:213], v[64:67]
	v_mfma_f32_16x16x32_bf16 v[116:119], v[170:173], v[186:189], v[116:119]
	v_mfma_f32_16x16x32_bf16 v[112:115], v[178:181], v[186:189], v[112:115]
	v_mfma_f32_16x16x32_bf16 v[100:103], v[170:173], v[198:201], v[100:103]
	v_mfma_f32_16x16x32_bf16 v[96:99], v[178:181], v[198:201], v[96:99]
	v_mfma_f32_16x16x32_bf16 v[84:87], v[170:173], v[206:209], v[84:87]
	v_mfma_f32_16x16x32_bf16 v[80:83], v[178:181], v[206:209], v[80:83]
	v_mfma_f32_16x16x32_bf16 v[68:71], v[170:173], v[214:217], v[68:71]
	v_mfma_f32_16x16x32_bf16 v[64:67], v[178:181], v[214:217], v[64:67]
	s_setprio 0
	s_barrier
	s_add_i32 s34, s57, s0
	s_mov_b32 m0, s34
	ds_read_b128 v[182:185], v153 offset:49152
	ds_read_b128 v[186:189], v153 offset:50176
	ds_read_b128 v[194:197], v153 offset:51200
	ds_read_b128 v[198:201], v153 offset:52224
	global_load_lds_dwordx4 v130, vcc
	s_add_i32 m0, s34, 0x2000
	s_add_u32 s28, s28, 0x100080
	s_addc_u32 s29, s29, 0
	s_add_i32 s34, s58, s0
	global_load_lds_dwordx4 v134, vcc
	s_mov_b32 m0, s34
	ds_read_b128 v[214:217], v153 offset:56320
	global_load_lds_dwordx4 v130, s[28:29]
	s_add_i32 m0, s34, 0x2000
	ds_read_b128 v[210:213], v153 offset:55296
	global_load_lds_dwordx4 v134, s[28:29]
	s_mov_b32 m0, s39
	ds_read_b128 v[206:209], v153 offset:54272
	global_load_lds_dwordx4 v128, s[100:101]
	s_mov_b32 m0, s40
	ds_read_b128 v[202:205], v153 offset:53248
	global_load_lds_dwordx4 v132, s[100:101]
	s_waitcnt vmcnt(8)
	s_waitcnt lgkmcnt(0)
	s_barrier
	s_setprio 1
	v_mfma_f32_16x16x32_bf16 v[60:63], v[144:147], v[182:185], v[60:63]
	v_mfma_f32_16x16x32_bf16 v[56:59], v[158:161], v[182:185], v[56:59]
	v_mfma_f32_16x16x32_bf16 v[44:47], v[144:147], v[194:197], v[44:47]
	v_mfma_f32_16x16x32_bf16 v[40:43], v[158:161], v[194:197], v[40:43]
	v_mfma_f32_16x16x32_bf16 v[28:31], v[144:147], v[202:205], v[28:31]
	v_mfma_f32_16x16x32_bf16 v[24:27], v[158:161], v[202:205], v[24:27]
	v_mfma_f32_16x16x32_bf16 v[12:15], v[144:147], v[210:213], v[12:15]
	v_mfma_f32_16x16x32_bf16 v[8:11], v[158:161], v[210:213], v[8:11]
	v_mfma_f32_16x16x32_bf16 v[60:63], v[154:157], v[186:189], v[60:63]
	v_mfma_f32_16x16x32_bf16 v[56:59], v[162:165], v[186:189], v[56:59]
	v_mfma_f32_16x16x32_bf16 v[44:47], v[154:157], v[198:201], v[44:47]
	v_mfma_f32_16x16x32_bf16 v[40:43], v[162:165], v[198:201], v[40:43]
	v_mfma_f32_16x16x32_bf16 v[28:31], v[154:157], v[206:209], v[28:31]
	v_mfma_f32_16x16x32_bf16 v[24:27], v[162:165], v[206:209], v[24:27]
	v_mfma_f32_16x16x32_bf16 v[12:15], v[154:157], v[214:217], v[12:15]
	v_mfma_f32_16x16x32_bf16 v[8:11], v[162:165], v[214:217], v[8:11]
	s_setprio 0
	s_setprio 1
	v_mfma_f32_16x16x32_bf16 v[52:55], v[166:169], v[182:185], v[52:55]
	v_mfma_f32_16x16x32_bf16 v[48:51], v[174:177], v[182:185], v[48:51]
	v_mfma_f32_16x16x32_bf16 v[36:39], v[166:169], v[194:197], v[36:39]
	v_mfma_f32_16x16x32_bf16 v[32:35], v[174:177], v[194:197], v[32:35]
	v_mfma_f32_16x16x32_bf16 v[20:23], v[166:169], v[202:205], v[20:23]
	v_mfma_f32_16x16x32_bf16 v[16:19], v[174:177], v[202:205], v[16:19]
	v_mfma_f32_16x16x32_bf16 v[4:7], v[166:169], v[210:213], v[4:7]
	v_mfma_f32_16x16x32_bf16 v[0:3], v[174:177], v[210:213], v[0:3]
	v_mfma_f32_16x16x32_bf16 v[52:55], v[170:173], v[186:189], v[52:55]
	v_mfma_f32_16x16x32_bf16 v[48:51], v[178:181], v[186:189], v[48:51]
	v_mfma_f32_16x16x32_bf16 v[36:39], v[170:173], v[198:201], v[36:39]
	v_mfma_f32_16x16x32_bf16 v[32:35], v[178:181], v[198:201], v[32:35]
	v_mfma_f32_16x16x32_bf16 v[20:23], v[170:173], v[206:209], v[20:23]
	v_mfma_f32_16x16x32_bf16 v[16:19], v[178:181], v[206:209], v[16:19]
	v_mfma_f32_16x16x32_bf16 v[4:7], v[170:173], v[214:217], v[4:7]
	v_mfma_f32_16x16x32_bf16 v[0:3], v[178:181], v[214:217], v[0:3]
	s_setprio 0
	s_barrier
	s_add_i32 s56, s56, 2
	s_add_u32 s26, s26, 0x100
	s_addc_u32 s27, s27, 0
	s_add_u32 s50, s50, 0x100
	s_addc_u32 s51, s51, 0
	s_cmp_gt_u32 s56, 61
	s_cbranch_scc0 .LBB0_501
	s_and_b64 vcc, exec, s[14:15]
	s_cbranch_vccz .LBB0_504
	s_barrier
